# T21: in-proj u/v/q epilogue bf16 stores widened to dwordx4 via v_permlane16_swap (half the store instructions, same bytes)
# speedup vs baseline: 1.0096x; 1.0091x over previous
.LBB0_602:
	s_cmp_lg_u32 s42, 2
	s_mov_b64 s[42:43], -1
	s_cbranch_scc0 .LBB0_604
	v_lshlrev_b64 v[130:131], 10, v[190:191]
	v_lshl_add_u64 v[130:131], s[34:35], 0, v[130:131]
	s_add_i32 s42, s6, 0xfffffd00
	s_mov_b32 s43, s55
	v_lshl_add_u64 v[130:131], s[42:43], 1, v[130:131]
	s_lshl_b32 s42, s76, 1
	v_lshl_add_u64 v[130:131], v[130:131], 0, s[42:43]
	v_lshlrev_b32_e32 v132, 1, v217
	v_mov_b32_e32 v133, v1
	v_lshl_add_u64 v[146:147], v[130:131], 0, v[132:133]
	global_load_dwordx4 v[130:133], v[188:189], off
	v_mov_b64_e32 v[164:165], 0
	v_mov_b64_e32 v[166:167], v[146:147]
	s_movk_i32 s5, 0x4000
	s_waitcnt vmcnt(0)
	v_mov_b32_e32 v134, v131
	v_mov_b32_e32 v135, v132
	v_mov_b32_e32 v131, v133
	v_pk_add_f32 v[130:131], v[134:135], v[130:131]
	s_nop 0
	v_add_f32_e32 v130, v130, v131
	v_fmamk_f32 v130, v130, 0x3a800000, v223
	v_rsq_f32_e32 v162, v130
	global_load_dwordx4 v[130:133], v[188:189], off offset:256
	s_waitcnt vmcnt(0)
	v_mov_b32_e32 v134, v131
	v_mov_b32_e32 v135, v132
	v_mov_b32_e32 v131, v133
	v_pk_add_f32 v[130:131], v[134:135], v[130:131]
	s_nop 0
	v_add_f32_e32 v130, v130, v131
	v_fmamk_f32 v130, v130, 0x3a800000, v223
	v_rsq_f32_e32 v160, v130
	global_load_dwordx4 v[130:133], v[188:189], off offset:512
	s_waitcnt vmcnt(0)
	v_mov_b32_e32 v134, v131
	v_mov_b32_e32 v135, v132
	v_mov_b32_e32 v131, v133
	v_pk_add_f32 v[130:131], v[134:135], v[130:131]
	s_nop 0
	v_add_f32_e32 v130, v130, v131
	v_fmamk_f32 v130, v130, 0x3a800000, v223
	v_rsq_f32_e32 v152, v130
	global_load_dwordx4 v[130:133], v[188:189], off offset:768
	s_waitcnt vmcnt(0)
	v_mov_b32_e32 v134, v131
	v_mov_b32_e32 v135, v132
	v_mov_b32_e32 v131, v133
	v_pk_add_f32 v[130:131], v[134:135], v[130:131]
	s_nop 0
	v_add_f32_e32 v130, v130, v131
	v_fmamk_f32 v130, v130, 0x3a800000, v223
	v_rsq_f32_e32 v158, v130
	global_load_dwordx4 v[130:133], v[188:189], off offset:2048
	s_waitcnt vmcnt(0)
	v_mov_b32_e32 v134, v131
	v_mov_b32_e32 v135, v132
	v_mov_b32_e32 v131, v133
	v_pk_add_f32 v[130:131], v[134:135], v[130:131]
	s_nop 0
	v_add_f32_e32 v130, v130, v131
	v_fmamk_f32 v130, v130, 0x3a800000, v223
	v_rsq_f32_e32 v154, v130
	global_load_dwordx4 v[130:133], v[188:189], off offset:2304
	s_waitcnt vmcnt(0)
	v_mov_b32_e32 v134, v131
	v_mov_b32_e32 v135, v132
	v_mov_b32_e32 v131, v133
	v_pk_add_f32 v[130:131], v[134:135], v[130:131]
	s_nop 0
	v_add_f32_e32 v130, v130, v131
	v_fmamk_f32 v130, v130, 0x3a800000, v223
	v_rsq_f32_e32 v150, v130
	global_load_dwordx4 v[130:133], v[188:189], off offset:2560
	s_waitcnt vmcnt(0)
	v_mov_b32_e32 v134, v131
	v_mov_b32_e32 v135, v132
	v_mov_b32_e32 v131, v133
	v_pk_add_f32 v[130:131], v[134:135], v[130:131]
	s_nop 0
	v_add_f32_e32 v130, v130, v131
	v_fmamk_f32 v130, v130, 0x3a800000, v223
	v_rsq_f32_e32 v148, v130
	global_load_dwordx4 v[130:133], v[188:189], off offset:2816
	s_waitcnt vmcnt(0)
	v_mov_b32_e32 v134, v131
	v_mov_b32_e32 v135, v132
	v_mov_b32_e32 v131, v133
	v_pk_add_f32 v[130:131], v[134:135], v[130:131]
	s_nop 0
	v_add_f32_e32 v130, v130, v131
	v_fmamk_f32 v130, v130, 0x3a800000, v223
	v_rsq_f32_e32 v156, v130
	global_load_dwordx4 v[142:145], v[186:187], off
	global_load_dwordx4 v[138:141], v[186:187], off offset:64
	global_load_dwordx4 v[134:137], v[186:187], off offset:512
	global_load_dwordx4 v[130:133], v[186:187], off offset:576
	s_waitcnt vmcnt(3)
	v_pk_fma_f32 v[168:169], v[126:127], v[162:163], v[142:143] op_sel_hi:[1,0,1]
	v_pk_fma_f32 v[164:165], v[128:129], v[162:163], v[144:145] op_sel_hi:[1,0,1]
	s_waitcnt vmcnt(2)
	v_pk_fma_f32 v[170:171], v[124:125], v[162:163], v[140:141] op_sel_hi:[1,0,1]
	v_pk_fma_f32 v[172:173], v[122:123], v[162:163], v[138:139] op_sel_hi:[1,0,1]
	s_waitcnt vmcnt(1)
	v_pk_fma_f32 v[174:175], v[120:121], v[162:163], v[136:137] op_sel_hi:[1,0,1]
	v_pk_fma_f32 v[176:177], v[118:119], v[162:163], v[134:135] op_sel_hi:[1,0,1]
	s_waitcnt vmcnt(0)
	v_pk_fma_f32 v[192:193], v[116:117], v[162:163], v[132:133] op_sel_hi:[1,0,1]
	v_pk_fma_f32 v[162:163], v[114:115], v[162:163], v[130:131] op_sel_hi:[1,0,1]
	v_cvt_pk_bf16_f32 v240, v168, v169
	v_cvt_pk_bf16_f32 v241, v164, v165
	v_mbcnt_lo_u32_b32 v0, -1, 0
	v_mbcnt_hi_u32_b32 v0, -1, v0
	v_bfe_u32 v0, v0, 4, 1
	v_mul_u32_u24_e32 v0, 24, v0
	v_lshl_add_u64 v[248:249], v[166:167], 0, v[0:1]
	v_cvt_pk_bf16_f32 v242, v172, v173
	v_cvt_pk_bf16_f32 v243, v170, v171
	s_nop 1
	v_permlane16_swap_b32_e32 v240, v242
	v_permlane16_swap_b32_e32 v241, v243
	global_store_dwordx4 v[248:249], v[240:243], off
	v_cvt_pk_bf16_f32 v244, v176, v177
	v_cvt_pk_bf16_f32 v245, v174, v175
	v_cvt_pk_bf16_f32 v246, v162, v163
	v_cvt_pk_bf16_f32 v247, v192, v193
	s_nop 1
	v_permlane16_swap_b32_e32 v244, v246
	v_permlane16_swap_b32_e32 v245, v247
	global_store_dwordx4 v[248:249], v[244:247], off offset:64
	v_mov_b64_e32 v[162:163], 0
	v_mov_b64_e32 v[164:165], v[146:147]
	v_pk_fma_f32 v[166:167], v[110:111], v[160:161], v[142:143] op_sel_hi:[1,0,1]
	v_pk_fma_f32 v[162:163], v[112:113], v[160:161], v[144:145] op_sel_hi:[1,0,1]
	v_cvt_pk_bf16_f32 v240, v166, v167
	v_pk_fma_f32 v[168:169], v[108:109], v[160:161], v[140:141] op_sel_hi:[1,0,1]
	v_cvt_pk_bf16_f32 v241, v162, v163
	v_add_co_u32_e32 v162, vcc, s5, v164
	v_pk_fma_f32 v[170:171], v[106:107], v[160:161], v[138:139] op_sel_hi:[1,0,1]
	s_nop 0
	v_addc_co_u32_e32 v163, vcc, 0, v165, vcc
	v_pk_fma_f32 v[172:173], v[104:105], v[160:161], v[136:137] op_sel_hi:[1,0,1]
	v_pk_fma_f32 v[174:175], v[102:103], v[160:161], v[134:135] op_sel_hi:[1,0,1]
	v_pk_fma_f32 v[176:177], v[100:101], v[160:161], v[132:133] op_sel_hi:[1,0,1]
	v_pk_fma_f32 v[160:161], v[98:99], v[160:161], v[130:131] op_sel_hi:[1,0,1]
	v_mbcnt_lo_u32_b32 v0, -1, 0
	v_mbcnt_hi_u32_b32 v0, -1, v0
	v_bfe_u32 v0, v0, 4, 1
	v_mul_u32_u24_e32 v0, 24, v0
	v_lshl_add_u64 v[248:249], v[162:163], 0, v[0:1]
	v_cvt_pk_bf16_f32 v242, v170, v171
	v_cvt_pk_bf16_f32 v243, v168, v169
	s_nop 1
	v_permlane16_swap_b32_e32 v240, v242
	v_permlane16_swap_b32_e32 v241, v243
	global_store_dwordx4 v[248:249], v[240:243], off
	v_cvt_pk_bf16_f32 v244, v174, v175
	v_cvt_pk_bf16_f32 v245, v172, v173
	v_cvt_pk_bf16_f32 v246, v160, v161
	v_cvt_pk_bf16_f32 v247, v176, v177
	s_nop 1
	v_permlane16_swap_b32_e32 v244, v246
	v_permlane16_swap_b32_e32 v245, v247
	global_store_dwordx4 v[248:249], v[244:247], off offset:64
	v_mov_b64_e32 v[160:161], 0
	v_mov_b64_e32 v[162:163], v[146:147]
	v_pk_fma_f32 v[164:165], v[94:95], v[152:153], v[142:143] op_sel_hi:[1,0,1]
	v_pk_fma_f32 v[160:161], v[96:97], v[152:153], v[144:145] op_sel_hi:[1,0,1]
	s_mov_b32 s5, 0x8000
	v_cvt_pk_bf16_f32 v240, v164, v165
	v_cvt_pk_bf16_f32 v241, v160, v161
	v_add_co_u32_e32 v160, vcc, s5, v162
	v_pk_fma_f32 v[166:167], v[92:93], v[152:153], v[140:141] op_sel_hi:[1,0,1]
	s_nop 0
	v_addc_co_u32_e32 v161, vcc, 0, v163, vcc
	v_pk_fma_f32 v[168:169], v[90:91], v[152:153], v[138:139] op_sel_hi:[1,0,1]
	v_pk_fma_f32 v[170:171], v[88:89], v[152:153], v[136:137] op_sel_hi:[1,0,1]
	v_pk_fma_f32 v[172:173], v[86:87], v[152:153], v[134:135] op_sel_hi:[1,0,1]
	v_pk_fma_f32 v[174:175], v[84:85], v[152:153], v[132:133] op_sel_hi:[1,0,1]
	v_pk_fma_f32 v[152:153], v[82:83], v[152:153], v[130:131] op_sel_hi:[1,0,1]
	v_mbcnt_lo_u32_b32 v0, -1, 0
	v_mbcnt_hi_u32_b32 v0, -1, v0
	v_bfe_u32 v0, v0, 4, 1
	v_mul_u32_u24_e32 v0, 24, v0
	v_lshl_add_u64 v[248:249], v[160:161], 0, v[0:1]
	v_cvt_pk_bf16_f32 v242, v168, v169
	v_cvt_pk_bf16_f32 v243, v166, v167
	s_nop 1
	v_permlane16_swap_b32_e32 v240, v242
	v_permlane16_swap_b32_e32 v241, v243
	global_store_dwordx4 v[248:249], v[240:243], off
	v_cvt_pk_bf16_f32 v244, v172, v173
	v_cvt_pk_bf16_f32 v245, v170, v171
	v_cvt_pk_bf16_f32 v246, v152, v153
	v_cvt_pk_bf16_f32 v247, v174, v175
	s_nop 1
	v_permlane16_swap_b32_e32 v244, v246
	v_permlane16_swap_b32_e32 v245, v247
	global_store_dwordx4 v[248:249], v[244:247], off offset:64
	v_mov_b64_e32 v[152:153], 0
	v_mov_b64_e32 v[160:161], v[146:147]
	v_pk_fma_f32 v[162:163], v[78:79], v[158:159], v[142:143] op_sel_hi:[1,0,1]
	v_pk_fma_f32 v[152:153], v[80:81], v[158:159], v[144:145] op_sel_hi:[1,0,1]
	s_mov_b32 s5, 0xc000
	v_cvt_pk_bf16_f32 v240, v162, v163
	v_cvt_pk_bf16_f32 v241, v152, v153
	v_add_co_u32_e32 v152, vcc, s5, v160
	v_pk_fma_f32 v[164:165], v[76:77], v[158:159], v[140:141] op_sel_hi:[1,0,1]
	s_nop 0
	v_addc_co_u32_e32 v153, vcc, 0, v161, vcc
	v_pk_fma_f32 v[166:167], v[74:75], v[158:159], v[138:139] op_sel_hi:[1,0,1]
	v_pk_fma_f32 v[168:169], v[72:73], v[158:159], v[136:137] op_sel_hi:[1,0,1]
	v_pk_fma_f32 v[170:171], v[70:71], v[158:159], v[134:135] op_sel_hi:[1,0,1]
	v_pk_fma_f32 v[172:173], v[68:69], v[158:159], v[132:133] op_sel_hi:[1,0,1]
	v_pk_fma_f32 v[158:159], v[66:67], v[158:159], v[130:131] op_sel_hi:[1,0,1]
	v_mbcnt_lo_u32_b32 v0, -1, 0
	v_mbcnt_hi_u32_b32 v0, -1, v0
	v_bfe_u32 v0, v0, 4, 1
	v_mul_u32_u24_e32 v0, 24, v0
	v_lshl_add_u64 v[248:249], v[152:153], 0, v[0:1]
	v_cvt_pk_bf16_f32 v242, v166, v167
	v_cvt_pk_bf16_f32 v243, v164, v165
	s_nop 1
	v_permlane16_swap_b32_e32 v240, v242
	v_permlane16_swap_b32_e32 v241, v243
	global_store_dwordx4 v[248:249], v[240:243], off
	v_cvt_pk_bf16_f32 v244, v170, v171
	v_cvt_pk_bf16_f32 v245, v168, v169
	v_cvt_pk_bf16_f32 v246, v158, v159
	v_cvt_pk_bf16_f32 v247, v172, v173
	s_nop 1
	v_permlane16_swap_b32_e32 v244, v246
	v_permlane16_swap_b32_e32 v245, v247
	global_store_dwordx4 v[248:249], v[244:247], off offset:64
	v_mov_b64_e32 v[152:153], 0
	v_mov_b64_e32 v[158:159], v[146:147]
	v_pk_fma_f32 v[160:161], v[62:63], v[154:155], v[142:143] op_sel_hi:[1,0,1]
	v_pk_fma_f32 v[152:153], v[64:65], v[154:155], v[144:145] op_sel_hi:[1,0,1]
	s_mov_b32 s5, 0x20000
	v_cvt_pk_bf16_f32 v240, v160, v161
	v_cvt_pk_bf16_f32 v241, v152, v153
	v_add_co_u32_e32 v152, vcc, s5, v158
	v_pk_fma_f32 v[162:163], v[60:61], v[154:155], v[140:141] op_sel_hi:[1,0,1]
	s_nop 0
	v_addc_co_u32_e32 v153, vcc, 0, v159, vcc
	v_pk_fma_f32 v[164:165], v[58:59], v[154:155], v[138:139] op_sel_hi:[1,0,1]
	v_pk_fma_f32 v[166:167], v[56:57], v[154:155], v[136:137] op_sel_hi:[1,0,1]
	v_pk_fma_f32 v[168:169], v[54:55], v[154:155], v[134:135] op_sel_hi:[1,0,1]
	v_pk_fma_f32 v[170:171], v[52:53], v[154:155], v[132:133] op_sel_hi:[1,0,1]
	v_pk_fma_f32 v[154:155], v[50:51], v[154:155], v[130:131] op_sel_hi:[1,0,1]
	v_mbcnt_lo_u32_b32 v0, -1, 0
	v_mbcnt_hi_u32_b32 v0, -1, v0
	v_bfe_u32 v0, v0, 4, 1
	v_mul_u32_u24_e32 v0, 24, v0
	v_lshl_add_u64 v[248:249], v[152:153], 0, v[0:1]
	v_cvt_pk_bf16_f32 v242, v164, v165
	v_cvt_pk_bf16_f32 v243, v162, v163
	s_nop 1
	v_permlane16_swap_b32_e32 v240, v242
	v_permlane16_swap_b32_e32 v241, v243
	global_store_dwordx4 v[248:249], v[240:243], off
	v_cvt_pk_bf16_f32 v244, v168, v169
	v_cvt_pk_bf16_f32 v245, v166, v167
	v_cvt_pk_bf16_f32 v246, v154, v155
	v_cvt_pk_bf16_f32 v247, v170, v171
	s_nop 1
	v_permlane16_swap_b32_e32 v244, v246
	v_permlane16_swap_b32_e32 v245, v247
	global_store_dwordx4 v[248:249], v[244:247], off offset:64
	v_mov_b64_e32 v[152:153], 0
	v_mov_b64_e32 v[154:155], v[146:147]
	v_pk_fma_f32 v[158:159], v[46:47], v[150:151], v[142:143] op_sel_hi:[1,0,1]
	v_pk_fma_f32 v[152:153], v[48:49], v[150:151], v[144:145] op_sel_hi:[1,0,1]
	s_mov_b32 s5, 0x24000
	v_cvt_pk_bf16_f32 v240, v158, v159
	v_cvt_pk_bf16_f32 v241, v152, v153
	v_add_co_u32_e32 v152, vcc, s5, v154
	v_pk_fma_f32 v[160:161], v[44:45], v[150:151], v[140:141] op_sel_hi:[1,0,1]
	s_nop 0
	v_addc_co_u32_e32 v153, vcc, 0, v155, vcc
	v_pk_fma_f32 v[162:163], v[42:43], v[150:151], v[138:139] op_sel_hi:[1,0,1]
	v_pk_fma_f32 v[164:165], v[40:41], v[150:151], v[136:137] op_sel_hi:[1,0,1]
	v_pk_fma_f32 v[166:167], v[38:39], v[150:151], v[134:135] op_sel_hi:[1,0,1]
	v_pk_fma_f32 v[168:169], v[36:37], v[150:151], v[132:133] op_sel_hi:[1,0,1]
	v_pk_fma_f32 v[150:151], v[34:35], v[150:151], v[130:131] op_sel_hi:[1,0,1]
	v_mbcnt_lo_u32_b32 v0, -1, 0
	v_mbcnt_hi_u32_b32 v0, -1, v0
	v_bfe_u32 v0, v0, 4, 1
	v_mul_u32_u24_e32 v0, 24, v0
	v_lshl_add_u64 v[248:249], v[152:153], 0, v[0:1]
	v_cvt_pk_bf16_f32 v242, v162, v163
	v_cvt_pk_bf16_f32 v243, v160, v161
	s_nop 1
	v_permlane16_swap_b32_e32 v240, v242
	v_permlane16_swap_b32_e32 v241, v243
	global_store_dwordx4 v[248:249], v[240:243], off
	v_cvt_pk_bf16_f32 v244, v166, v167
	v_cvt_pk_bf16_f32 v245, v164, v165
	v_cvt_pk_bf16_f32 v246, v150, v151
	v_cvt_pk_bf16_f32 v247, v168, v169
	s_nop 1
	v_permlane16_swap_b32_e32 v244, v246
	v_permlane16_swap_b32_e32 v245, v247
	global_store_dwordx4 v[248:249], v[244:247], off offset:64
	v_mov_b64_e32 v[150:151], 0
	v_mov_b64_e32 v[152:153], v[146:147]
	v_pk_fma_f32 v[154:155], v[30:31], v[148:149], v[142:143] op_sel_hi:[1,0,1]
	v_pk_fma_f32 v[150:151], v[32:33], v[148:149], v[144:145] op_sel_hi:[1,0,1]
	s_mov_b32 s5, 0x28000
	v_cvt_pk_bf16_f32 v240, v154, v155
	v_cvt_pk_bf16_f32 v241, v150, v151
	v_add_co_u32_e32 v150, vcc, s5, v152
	v_pk_fma_f32 v[158:159], v[28:29], v[148:149], v[140:141] op_sel_hi:[1,0,1]
	s_nop 0
	v_addc_co_u32_e32 v151, vcc, 0, v153, vcc
	v_pk_fma_f32 v[160:161], v[26:27], v[148:149], v[138:139] op_sel_hi:[1,0,1]
	v_mbcnt_lo_u32_b32 v0, -1, 0
	v_mbcnt_hi_u32_b32 v0, -1, v0
	v_bfe_u32 v0, v0, 4, 1
	v_mul_u32_u24_e32 v0, 24, v0
	v_lshl_add_u64 v[248:249], v[150:151], 0, v[0:1]
	v_cvt_pk_bf16_f32 v242, v160, v161
	v_cvt_pk_bf16_f32 v243, v158, v159
	v_pk_fma_f32 v[162:163], v[24:25], v[148:149], v[136:137] op_sel_hi:[1,0,1]
	v_pk_fma_f32 v[164:165], v[22:23], v[148:149], v[134:135] op_sel_hi:[1,0,1]
	s_nop 1
	v_permlane16_swap_b32_e32 v240, v242
	v_permlane16_swap_b32_e32 v241, v243
	global_store_dwordx4 v[248:249], v[240:243], off
	v_cvt_pk_bf16_f32 v244, v164, v165
	v_cvt_pk_bf16_f32 v245, v162, v163
	v_pk_fma_f32 v[166:167], v[20:21], v[148:149], v[132:133] op_sel_hi:[1,0,1]
	v_pk_fma_f32 v[168:169], v[18:19], v[148:149], v[130:131] op_sel_hi:[1,0,1]
	v_cvt_pk_bf16_f32 v246, v168, v169
	v_cvt_pk_bf16_f32 v247, v166, v167
	s_nop 1
	v_permlane16_swap_b32_e32 v244, v246
	v_permlane16_swap_b32_e32 v245, v247
	global_store_dwordx4 v[248:249], v[244:247], off offset:64
	v_mov_b64_e32 v[150:151], 0
	v_pk_fma_f32 v[144:145], v[16:17], v[156:157], v[144:145] op_sel_hi:[1,0,1]
	v_pk_fma_f32 v[142:143], v[14:15], v[156:157], v[142:143] op_sel_hi:[1,0,1]
	s_mov_b32 s5, 0x2c000
	v_cvt_pk_bf16_f32 v240, v142, v143
	v_cvt_pk_bf16_f32 v241, v144, v145
	v_pk_fma_f32 v[138:139], v[10:11], v[156:157], v[138:139] op_sel_hi:[1,0,1]
	v_add_co_u32_e32 v144, vcc, s5, v146
	v_pk_fma_f32 v[134:135], v[6:7], v[156:157], v[134:135] op_sel_hi:[1,0,1]
	v_pk_fma_f32 v[130:131], v[2:3], v[156:157], v[130:131] op_sel_hi:[1,0,1]
	v_addc_co_u32_e32 v145, vcc, 0, v147, vcc
	v_pk_fma_f32 v[140:141], v[12:13], v[156:157], v[140:141] op_sel_hi:[1,0,1]
	v_pk_fma_f32 v[136:137], v[8:9], v[156:157], v[136:137] op_sel_hi:[1,0,1]
	v_pk_fma_f32 v[132:133], v[4:5], v[156:157], v[132:133] op_sel_hi:[1,0,1]
	v_mbcnt_lo_u32_b32 v0, -1, 0
	v_mbcnt_hi_u32_b32 v0, -1, v0
	v_bfe_u32 v0, v0, 4, 1
	v_mul_u32_u24_e32 v0, 24, v0
	v_lshl_add_u64 v[248:249], v[144:145], 0, v[0:1]
	v_cvt_pk_bf16_f32 v242, v138, v139
	v_cvt_pk_bf16_f32 v243, v140, v141
	s_nop 1
	v_permlane16_swap_b32_e32 v240, v242
	v_permlane16_swap_b32_e32 v241, v243
	global_store_dwordx4 v[248:249], v[240:243], off
	v_cvt_pk_bf16_f32 v244, v134, v135
	v_cvt_pk_bf16_f32 v245, v136, v137
	v_cvt_pk_bf16_f32 v246, v130, v131
	v_cvt_pk_bf16_f32 v247, v132, v133
	s_nop 1
	v_permlane16_swap_b32_e32 v244, v246
	v_permlane16_swap_b32_e32 v245, v247
	global_store_dwordx4 v[248:249], v[244:247], off offset:64
	s_mov_b64 s[42:43], 0

.LBB0_610:
	v_cvt_pk_bf16_f32 v240, v158, v159
	v_cvt_pk_bf16_f32 v241, v160, v161
	v_mbcnt_lo_u32_b32 v0, -1, 0
	v_mbcnt_hi_u32_b32 v0, -1, v0
	v_bfe_u32 v0, v0, 4, 1
	v_mul_u32_u24_e32 v0, 24, v0
	v_lshl_add_u64 v[248:249], v[176:177], 0, v[0:1]
	v_cvt_pk_bf16_f32 v242, v154, v155
	v_cvt_pk_bf16_f32 v243, v156, v157
	s_nop 1
	v_permlane16_swap_b32_e32 v240, v242
	v_permlane16_swap_b32_e32 v241, v243
	global_store_dwordx4 v[248:249], v[240:243], off
	v_cvt_pk_bf16_f32 v244, v150, v151
	v_cvt_pk_bf16_f32 v245, v152, v153
	v_cvt_pk_bf16_f32 v246, v146, v147
	v_cvt_pk_bf16_f32 v247, v148, v149
	s_nop 1
	v_permlane16_swap_b32_e32 v244, v246
	v_permlane16_swap_b32_e32 v245, v247
	global_store_dwordx4 v[248:249], v[244:247], off offset:64
	v_mov_b64_e32 v[176:177], v[192:193]
	v_mov_b64_e32 v[196:197], v[194:195]
	v_pk_fma_f32 v[160:161], v[112:113], v[174:175], v[144:145] op_sel_hi:[1,0,1]
	v_pk_fma_f32 v[158:159], v[110:111], v[174:175], v[142:143] op_sel_hi:[1,0,1]
	v_pk_fma_f32 v[156:157], v[108:109], v[174:175], v[140:141] op_sel_hi:[1,0,1]
	v_pk_fma_f32 v[154:155], v[106:107], v[174:175], v[138:139] op_sel_hi:[1,0,1]
	v_pk_fma_f32 v[152:153], v[104:105], v[174:175], v[136:137] op_sel_hi:[1,0,1]
	v_pk_fma_f32 v[150:151], v[102:103], v[174:175], v[134:135] op_sel_hi:[1,0,1]
	v_pk_fma_f32 v[148:149], v[100:101], v[174:175], v[132:133] op_sel_hi:[1,0,1]
	s_and_b64 vcc, exec, s[42:43]
	v_pk_fma_f32 v[146:147], v[98:99], v[174:175], v[130:131] op_sel_hi:[1,0,1]
	s_cbranch_vccnz .LBB0_612
	v_add_co_u32_e32 v174, vcc, 0x2000, v196
	s_nop 1
	v_addc_co_u32_e32 v175, vcc, 0, v197, vcc
	global_store_dwordx4 v[174:175], v[158:161], off
	global_store_dwordx4 v[174:175], v[154:157], off offset:64
	global_store_dwordx4 v[174:175], v[150:153], off offset:128
	global_store_dwordx4 v[174:175], v[146:149], off offset:192
.LBB0_612:
	v_cvt_pk_bf16_f32 v240, v158, v159
	v_cvt_pk_bf16_f32 v241, v160, v161
	v_add_co_u32_e32 v160, vcc, 0x1000, v176
	s_nop 1
	v_addc_co_u32_e32 v161, vcc, 0, v177, vcc
	v_mbcnt_lo_u32_b32 v0, -1, 0
	v_mbcnt_hi_u32_b32 v0, -1, v0
	v_bfe_u32 v0, v0, 4, 1
	v_mul_u32_u24_e32 v0, 24, v0
	v_lshl_add_u64 v[248:249], v[160:161], 0, v[0:1]
	v_cvt_pk_bf16_f32 v242, v154, v155
	v_cvt_pk_bf16_f32 v243, v156, v157
	s_nop 1
	v_permlane16_swap_b32_e32 v240, v242
	v_permlane16_swap_b32_e32 v241, v243
	global_store_dwordx4 v[248:249], v[240:243], off
	v_cvt_pk_bf16_f32 v244, v150, v151
	v_cvt_pk_bf16_f32 v245, v152, v153
	v_cvt_pk_bf16_f32 v246, v146, v147
	v_cvt_pk_bf16_f32 v247, v148, v149
	s_nop 1
	v_permlane16_swap_b32_e32 v244, v246
	v_permlane16_swap_b32_e32 v245, v247
	global_store_dwordx4 v[248:249], v[244:247], off offset:64
	v_mov_b64_e32 v[176:177], v[194:195]
	v_mov_b64_e32 v[174:175], v[192:193]
	v_pk_fma_f32 v[160:161], v[96:97], v[172:173], v[144:145] op_sel_hi:[1,0,1]
	v_pk_fma_f32 v[158:159], v[94:95], v[172:173], v[142:143] op_sel_hi:[1,0,1]
	v_pk_fma_f32 v[148:149], v[92:93], v[172:173], v[140:141] op_sel_hi:[1,0,1]
	v_pk_fma_f32 v[146:147], v[90:91], v[172:173], v[138:139] op_sel_hi:[1,0,1]
	v_pk_fma_f32 v[152:153], v[88:89], v[172:173], v[136:137] op_sel_hi:[1,0,1]
	v_pk_fma_f32 v[150:151], v[86:87], v[172:173], v[134:135] op_sel_hi:[1,0,1]
	v_pk_fma_f32 v[156:157], v[84:85], v[172:173], v[132:133] op_sel_hi:[1,0,1]
	s_and_b64 vcc, exec, s[42:43]
	v_pk_fma_f32 v[154:155], v[82:83], v[172:173], v[130:131] op_sel_hi:[1,0,1]
	s_cbranch_vccnz .LBB0_614
	v_add_co_u32_e32 v172, vcc, 0x4000, v176
	s_nop 1
	v_addc_co_u32_e32 v173, vcc, 0, v177, vcc
	global_store_dwordx4 v[172:173], v[158:161], off
	global_store_dwordx4 v[172:173], v[146:149], off offset:64
	global_store_dwordx4 v[172:173], v[150:153], off offset:128
	global_store_dwordx4 v[172:173], v[154:157], off offset:192
.LBB0_614:
	v_cvt_pk_bf16_f32 v240, v158, v159
	v_cvt_pk_bf16_f32 v241, v160, v161
	v_add_co_u32_e32 v160, vcc, 0x2000, v174
	v_mov_b64_e32 v[172:173], v[192:193]
	s_nop 0
	v_addc_co_u32_e32 v161, vcc, 0, v175, vcc
	v_mbcnt_lo_u32_b32 v0, -1, 0
	v_mbcnt_hi_u32_b32 v0, -1, v0
	v_bfe_u32 v0, v0, 4, 1
	v_mul_u32_u24_e32 v0, 24, v0
	v_lshl_add_u64 v[248:249], v[160:161], 0, v[0:1]
	v_cvt_pk_bf16_f32 v242, v146, v147
	v_cvt_pk_bf16_f32 v243, v148, v149
	s_nop 1
	v_permlane16_swap_b32_e32 v240, v242
	v_permlane16_swap_b32_e32 v241, v243
	global_store_dwordx4 v[248:249], v[240:243], off
	v_cvt_pk_bf16_f32 v244, v150, v151
	v_cvt_pk_bf16_f32 v245, v152, v153
	v_cvt_pk_bf16_f32 v246, v154, v155
	v_cvt_pk_bf16_f32 v247, v156, v157
	s_nop 1
	v_permlane16_swap_b32_e32 v244, v246
	v_permlane16_swap_b32_e32 v245, v247
	global_store_dwordx4 v[248:249], v[244:247], off offset:64
	v_mov_b64_e32 v[174:175], v[194:195]
	v_pk_fma_f32 v[160:161], v[80:81], v[170:171], v[144:145] op_sel_hi:[1,0,1]
	v_pk_fma_f32 v[158:159], v[78:79], v[170:171], v[142:143] op_sel_hi:[1,0,1]
	v_pk_fma_f32 v[156:157], v[76:77], v[170:171], v[140:141] op_sel_hi:[1,0,1]
	v_pk_fma_f32 v[154:155], v[74:75], v[170:171], v[138:139] op_sel_hi:[1,0,1]
	v_pk_fma_f32 v[152:153], v[72:73], v[170:171], v[136:137] op_sel_hi:[1,0,1]
	v_pk_fma_f32 v[150:151], v[70:71], v[170:171], v[134:135] op_sel_hi:[1,0,1]
	v_pk_fma_f32 v[148:149], v[68:69], v[170:171], v[132:133] op_sel_hi:[1,0,1]
	s_and_b64 vcc, exec, s[42:43]
	v_pk_fma_f32 v[146:147], v[66:67], v[170:171], v[130:131] op_sel_hi:[1,0,1]
	s_cbranch_vccnz .LBB0_616
	v_add_co_u32_e32 v170, vcc, 0x6000, v174
	s_nop 1
	v_addc_co_u32_e32 v171, vcc, 0, v175, vcc
	global_store_dwordx4 v[170:171], v[158:161], off
	global_store_dwordx4 v[170:171], v[154:157], off offset:64
	global_store_dwordx4 v[170:171], v[150:153], off offset:128
	global_store_dwordx4 v[170:171], v[146:149], off offset:192
.LBB0_616:
	v_cvt_pk_bf16_f32 v240, v158, v159
	v_cvt_pk_bf16_f32 v241, v160, v161
	v_add_co_u32_e32 v160, vcc, 0x3000, v172
	s_nop 1
	v_addc_co_u32_e32 v161, vcc, 0, v173, vcc
	v_mbcnt_lo_u32_b32 v0, -1, 0
	v_mbcnt_hi_u32_b32 v0, -1, v0
	v_bfe_u32 v0, v0, 4, 1
	v_mul_u32_u24_e32 v0, 24, v0
	v_lshl_add_u64 v[248:249], v[160:161], 0, v[0:1]
	v_cvt_pk_bf16_f32 v242, v154, v155
	v_cvt_pk_bf16_f32 v243, v156, v157
	s_nop 1
	v_permlane16_swap_b32_e32 v240, v242
	v_permlane16_swap_b32_e32 v241, v243
	global_store_dwordx4 v[248:249], v[240:243], off
	v_cvt_pk_bf16_f32 v244, v150, v151
	v_cvt_pk_bf16_f32 v245, v152, v153
	v_cvt_pk_bf16_f32 v246, v146, v147
	v_cvt_pk_bf16_f32 v247, v148, v149
	s_nop 1
	v_permlane16_swap_b32_e32 v244, v246
	v_permlane16_swap_b32_e32 v245, v247
	global_store_dwordx4 v[248:249], v[244:247], off offset:64
	v_mov_b64_e32 v[170:171], v[192:193]
	v_mov_b64_e32 v[172:173], v[194:195]
	v_pk_fma_f32 v[160:161], v[64:65], v[168:169], v[144:145] op_sel_hi:[1,0,1]
	v_pk_fma_f32 v[158:159], v[62:63], v[168:169], v[142:143] op_sel_hi:[1,0,1]
	v_pk_fma_f32 v[148:149], v[60:61], v[168:169], v[140:141] op_sel_hi:[1,0,1]
	v_pk_fma_f32 v[146:147], v[58:59], v[168:169], v[138:139] op_sel_hi:[1,0,1]
	v_pk_fma_f32 v[152:153], v[56:57], v[168:169], v[136:137] op_sel_hi:[1,0,1]
	v_pk_fma_f32 v[150:151], v[54:55], v[168:169], v[134:135] op_sel_hi:[1,0,1]
	v_pk_fma_f32 v[156:157], v[52:53], v[168:169], v[132:133] op_sel_hi:[1,0,1]
	s_and_b64 vcc, exec, s[42:43]
	v_pk_fma_f32 v[154:155], v[50:51], v[168:169], v[130:131] op_sel_hi:[1,0,1]
	s_cbranch_vccnz .LBB0_618
	v_add_co_u32_e32 v168, vcc, 0x10000, v172
	s_nop 1
	v_addc_co_u32_e32 v169, vcc, 0, v173, vcc
	global_store_dwordx4 v[168:169], v[158:161], off
	global_store_dwordx4 v[168:169], v[146:149], off offset:64
	global_store_dwordx4 v[168:169], v[150:153], off offset:128
	global_store_dwordx4 v[168:169], v[154:157], off offset:192
.LBB0_618:
	v_cvt_pk_bf16_f32 v240, v158, v159
	v_cvt_pk_bf16_f32 v241, v160, v161
	v_add_co_u32_e32 v160, vcc, 0x8000, v170
	v_mov_b64_e32 v[168:169], v[192:193]
	s_nop 0
	v_addc_co_u32_e32 v161, vcc, 0, v171, vcc
	v_mbcnt_lo_u32_b32 v0, -1, 0
	v_mbcnt_hi_u32_b32 v0, -1, v0
	v_bfe_u32 v0, v0, 4, 1
	v_mul_u32_u24_e32 v0, 24, v0
	v_lshl_add_u64 v[248:249], v[160:161], 0, v[0:1]
	v_cvt_pk_bf16_f32 v242, v146, v147
	v_cvt_pk_bf16_f32 v243, v148, v149
	s_nop 1
	v_permlane16_swap_b32_e32 v240, v242
	v_permlane16_swap_b32_e32 v241, v243
	global_store_dwordx4 v[248:249], v[240:243], off
	v_cvt_pk_bf16_f32 v244, v150, v151
	v_cvt_pk_bf16_f32 v245, v152, v153
	v_cvt_pk_bf16_f32 v246, v154, v155
	v_cvt_pk_bf16_f32 v247, v156, v157
	s_nop 1
	v_permlane16_swap_b32_e32 v244, v246
	v_permlane16_swap_b32_e32 v245, v247
	global_store_dwordx4 v[248:249], v[244:247], off offset:64
	v_mov_b64_e32 v[170:171], v[194:195]
	v_pk_fma_f32 v[160:161], v[48:49], v[166:167], v[144:145] op_sel_hi:[1,0,1]
	v_pk_fma_f32 v[158:159], v[46:47], v[166:167], v[142:143] op_sel_hi:[1,0,1]
	v_pk_fma_f32 v[156:157], v[44:45], v[166:167], v[140:141] op_sel_hi:[1,0,1]
	v_pk_fma_f32 v[154:155], v[42:43], v[166:167], v[138:139] op_sel_hi:[1,0,1]
	v_pk_fma_f32 v[152:153], v[40:41], v[166:167], v[136:137] op_sel_hi:[1,0,1]
	v_pk_fma_f32 v[150:151], v[38:39], v[166:167], v[134:135] op_sel_hi:[1,0,1]
	v_pk_fma_f32 v[148:149], v[36:37], v[166:167], v[132:133] op_sel_hi:[1,0,1]
	s_and_b64 vcc, exec, s[42:43]
	v_pk_fma_f32 v[146:147], v[34:35], v[166:167], v[130:131] op_sel_hi:[1,0,1]
	s_cbranch_vccnz .LBB0_620
	v_add_co_u32_e32 v166, vcc, 0x12000, v170
	s_nop 1
	v_addc_co_u32_e32 v167, vcc, 0, v171, vcc
	global_store_dwordx4 v[166:167], v[158:161], off
	global_store_dwordx4 v[166:167], v[154:157], off offset:64
	global_store_dwordx4 v[166:167], v[150:153], off offset:128
	global_store_dwordx4 v[166:167], v[146:149], off offset:192
.LBB0_620:
	v_cvt_pk_bf16_f32 v240, v158, v159
	v_cvt_pk_bf16_f32 v241, v160, v161
	v_add_co_u32_e32 v160, vcc, 0x9000, v168
	s_nop 1
	v_addc_co_u32_e32 v161, vcc, 0, v169, vcc
	v_mbcnt_lo_u32_b32 v0, -1, 0
	v_mbcnt_hi_u32_b32 v0, -1, v0
	v_bfe_u32 v0, v0, 4, 1
	v_mul_u32_u24_e32 v0, 24, v0
	v_lshl_add_u64 v[248:249], v[160:161], 0, v[0:1]
	v_cvt_pk_bf16_f32 v242, v154, v155
	v_cvt_pk_bf16_f32 v243, v156, v157
	s_nop 1
	v_permlane16_swap_b32_e32 v240, v242
	v_permlane16_swap_b32_e32 v241, v243
	global_store_dwordx4 v[248:249], v[240:243], off
	v_cvt_pk_bf16_f32 v244, v150, v151
	v_cvt_pk_bf16_f32 v245, v152, v153
	v_cvt_pk_bf16_f32 v246, v146, v147
	v_cvt_pk_bf16_f32 v247, v148, v149
	s_nop 1
	v_permlane16_swap_b32_e32 v244, v246
	v_permlane16_swap_b32_e32 v245, v247
	global_store_dwordx4 v[248:249], v[244:247], off offset:64
	v_mov_b64_e32 v[168:169], v[194:195]
	v_mov_b64_e32 v[166:167], v[192:193]
	v_pk_fma_f32 v[160:161], v[32:33], v[164:165], v[144:145] op_sel_hi:[1,0,1]
	v_pk_fma_f32 v[158:159], v[30:31], v[164:165], v[142:143] op_sel_hi:[1,0,1]
	v_pk_fma_f32 v[148:149], v[28:29], v[164:165], v[140:141] op_sel_hi:[1,0,1]
	v_pk_fma_f32 v[146:147], v[26:27], v[164:165], v[138:139] op_sel_hi:[1,0,1]
	v_pk_fma_f32 v[152:153], v[24:25], v[164:165], v[136:137] op_sel_hi:[1,0,1]
	v_pk_fma_f32 v[150:151], v[22:23], v[164:165], v[134:135] op_sel_hi:[1,0,1]
	v_pk_fma_f32 v[156:157], v[20:21], v[164:165], v[132:133] op_sel_hi:[1,0,1]
	s_and_b64 vcc, exec, s[42:43]
	v_pk_fma_f32 v[154:155], v[18:19], v[164:165], v[130:131] op_sel_hi:[1,0,1]
	s_cbranch_vccnz .LBB0_622
	v_add_co_u32_e32 v164, vcc, 0x14000, v168
	s_nop 1
	v_addc_co_u32_e32 v165, vcc, 0, v169, vcc
	global_store_dwordx4 v[164:165], v[158:161], off
	global_store_dwordx4 v[164:165], v[146:149], off offset:64
	global_store_dwordx4 v[164:165], v[150:153], off offset:128
	global_store_dwordx4 v[164:165], v[154:157], off offset:192
.LBB0_622:
	v_cvt_pk_bf16_f32 v240, v158, v159
	v_cvt_pk_bf16_f32 v241, v160, v161
	v_add_co_u32_e32 v160, vcc, 0xa000, v166
	v_pk_fma_f32 v[144:145], v[16:17], v[162:163], v[144:145] op_sel_hi:[1,0,1]
	s_nop 0
	v_addc_co_u32_e32 v161, vcc, 0, v167, vcc
	v_mbcnt_lo_u32_b32 v0, -1, 0
	v_mbcnt_hi_u32_b32 v0, -1, v0
	v_bfe_u32 v0, v0, 4, 1
	v_mul_u32_u24_e32 v0, 24, v0
	v_lshl_add_u64 v[248:249], v[160:161], 0, v[0:1]
	v_cvt_pk_bf16_f32 v242, v146, v147
	v_cvt_pk_bf16_f32 v243, v148, v149
	s_nop 1
	v_permlane16_swap_b32_e32 v240, v242
	v_permlane16_swap_b32_e32 v241, v243
	global_store_dwordx4 v[248:249], v[240:243], off
	v_cvt_pk_bf16_f32 v244, v150, v151
	v_cvt_pk_bf16_f32 v245, v152, v153
	v_cvt_pk_bf16_f32 v246, v154, v155
	v_cvt_pk_bf16_f32 v247, v156, v157
	s_nop 1
	v_permlane16_swap_b32_e32 v244, v246
	v_permlane16_swap_b32_e32 v245, v247
	global_store_dwordx4 v[248:249], v[244:247], off offset:64
	v_mov_b64_e32 v[148:149], v[194:195]
	v_mov_b64_e32 v[146:147], v[192:193]
	v_pk_fma_f32 v[142:143], v[14:15], v[162:163], v[142:143] op_sel_hi:[1,0,1]
	v_pk_fma_f32 v[140:141], v[12:13], v[162:163], v[140:141] op_sel_hi:[1,0,1]
	v_pk_fma_f32 v[138:139], v[10:11], v[162:163], v[138:139] op_sel_hi:[1,0,1]
	v_pk_fma_f32 v[136:137], v[8:9], v[162:163], v[136:137] op_sel_hi:[1,0,1]
	v_pk_fma_f32 v[134:135], v[6:7], v[162:163], v[134:135] op_sel_hi:[1,0,1]
	v_pk_fma_f32 v[132:133], v[4:5], v[162:163], v[132:133] op_sel_hi:[1,0,1]
	s_and_b64 vcc, exec, s[42:43]
	v_pk_fma_f32 v[130:131], v[2:3], v[162:163], v[130:131] op_sel_hi:[1,0,1]
	s_cbranch_vccnz .LBB0_624
	v_add_co_u32_e32 v148, vcc, 0x16000, v148
	s_nop 1
	v_addc_co_u32_e32 v149, vcc, 0, v149, vcc
	global_store_dwordx4 v[148:149], v[142:145], off
	global_store_dwordx4 v[148:149], v[138:141], off offset:64
	global_store_dwordx4 v[148:149], v[134:137], off offset:128
	global_store_dwordx4 v[148:149], v[130:133], off offset:192
.LBB0_624:
	v_cvt_pk_bf16_f32 v240, v142, v143
	v_cvt_pk_bf16_f32 v241, v144, v145
	v_add_co_u32_e32 v144, vcc, 0xb000, v146
	s_nop 1
	v_addc_co_u32_e32 v145, vcc, 0, v147, vcc
	v_mbcnt_lo_u32_b32 v0, -1, 0
	v_mbcnt_hi_u32_b32 v0, -1, v0
	v_bfe_u32 v0, v0, 4, 1
	v_mul_u32_u24_e32 v0, 24, v0
	v_lshl_add_u64 v[248:249], v[144:145], 0, v[0:1]
	v_cvt_pk_bf16_f32 v242, v138, v139
	v_cvt_pk_bf16_f32 v243, v140, v141
	s_nop 1
	v_permlane16_swap_b32_e32 v240, v242
	v_permlane16_swap_b32_e32 v241, v243
	global_store_dwordx4 v[248:249], v[240:243], off
	v_cvt_pk_bf16_f32 v244, v134, v135
	v_cvt_pk_bf16_f32 v245, v136, v137
	v_cvt_pk_bf16_f32 v246, v130, v131
	v_cvt_pk_bf16_f32 v247, v132, v133
	s_nop 1
	v_permlane16_swap_b32_e32 v244, v246
	v_permlane16_swap_b32_e32 v245, v247
	global_store_dwordx4 v[248:249], v[244:247], off offset:64
	s_mov_b64 s[56:57], 0

.LBB0_662:
	v_pk_mul_f32 v[120:121], v[120:121], s[12:13] op_sel_hi:[1,0]
	v_pk_mul_f32 v[128:129], v[128:129], s[12:13] op_sel_hi:[1,0]
	v_pk_mul_f32 v[116:117], v[116:117], s[12:13] op_sel_hi:[1,0]
	v_pk_mul_f32 v[126:127], v[126:127], s[12:13] op_sel_hi:[1,0]
	v_cvt_pk_bf16_f32 v240, v128, v129
	v_cvt_pk_bf16_f32 v241, v120, v121
	v_mbcnt_lo_u32_b32 v252, -1, 0
	v_mbcnt_hi_u32_b32 v252, -1, v252
	v_bfe_u32 v252, v252, 4, 1
	v_mul_u32_u24_e32 v252, 24, v252
	v_mov_b32_e32 v253, 0
	v_lshl_add_u64 v[248:249], v[186:187], 0, v[252:253]
	v_cvt_pk_bf16_f32 v242, v126, v127
	v_cvt_pk_bf16_f32 v243, v116, v117
	v_pk_fma_f32 v[112:113], v[112:113], v[176:177], v[160:161] op_sel_hi:[1,0,1]
	v_pk_fma_f32 v[110:111], v[110:111], v[176:177], v[158:159] op_sel_hi:[1,0,1]
	s_nop 1
	v_permlane16_swap_b32_e32 v240, v242
	v_permlane16_swap_b32_e32 v241, v243
	global_store_dwordx4 v[248:249], v[240:243], off
	v_pk_fma_f32 v[120:121], v[98:99], v[176:177], v[146:147] op_sel_hi:[1,0,1]
	v_mul_f32_e32 v98, v111, v111
	v_mul_f32_e32 v99, v113, v113
	v_pk_mul_f32 v[118:119], v[118:119], s[12:13] op_sel_hi:[1,0]
	v_pk_fma_f32 v[108:109], v[108:109], v[176:177], v[156:157] op_sel_hi:[1,0,1]
	v_pk_fma_f32 v[106:107], v[106:107], v[176:177], v[154:155] op_sel_hi:[1,0,1]
	v_fmac_f32_e32 v98, v110, v110
	v_fmac_f32_e32 v99, v112, v112
	v_pk_mul_f32 v[122:123], v[122:123], s[12:13] op_sel_hi:[1,0]
	v_add_f32_e32 v98, v98, v99
	v_cvt_pk_bf16_f32 v244, v122, v123
	v_cvt_pk_bf16_f32 v245, v118, v119
	v_pk_fma_f32 v[118:119], v[100:101], v[176:177], v[148:149] op_sel_hi:[1,0,1]
	v_mul_f32_e32 v99, v107, v107
	v_mul_f32_e32 v100, v109, v109
	v_pk_mul_f32 v[114:115], v[114:115], s[12:13] op_sel_hi:[1,0]
	v_pk_mul_f32 v[124:125], v[124:125], s[12:13] op_sel_hi:[1,0]
	v_cvt_pk_bf16_f32 v246, v124, v125
	v_cvt_pk_bf16_f32 v247, v114, v115
	v_fmac_f32_e32 v99, v106, v106
	v_fmac_f32_e32 v100, v108, v108
	s_nop 1
	v_permlane16_swap_b32_e32 v244, v246
	v_permlane16_swap_b32_e32 v245, v247
	global_store_dwordx4 v[248:249], v[244:247], off offset:64
	v_pk_fma_f32 v[116:117], v[104:105], v[176:177], v[152:153] op_sel_hi:[1,0,1]
	v_pk_fma_f32 v[102:103], v[102:103], v[176:177], v[150:151] op_sel_hi:[1,0,1]
	v_add_f32_e32 v99, v99, v100
	v_add_f32_e32 v98, v98, v99
	v_mul_f32_e32 v99, v103, v103
	v_mul_f32_e32 v100, v117, v117
	v_fmac_f32_e32 v99, v102, v102
	v_fmac_f32_e32 v100, v116, v116
	v_add_f32_e32 v99, v99, v100
	v_add_f32_e32 v98, v98, v99
	v_mul_f32_e32 v99, v121, v121
	v_mul_f32_e32 v100, v119, v119
	v_fmac_f32_e32 v99, v120, v120
	v_fmac_f32_e32 v100, v118, v118
	v_add_f32_e32 v99, v99, v100
	v_add_f32_e32 v98, v98, v99
	v_mov_b32_e32 v99, v98
	s_nop 1
	v_permlane16_swap_b32_e32 v98, v99
	v_add_f32_e32 v98, v98, v99
	v_mov_b32_e32 v99, v98
	s_nop 1
	v_permlane32_swap_b32_e32 v98, v99
	v_add_f32_e32 v98, v98, v99
	v_fmamk_f32 v98, v98, 0x3c800000, v223
	v_rsq_f32_e32 v122, v98
	v_mov_b64_e32 v[100:101], 0
	v_mov_b64_e32 v[98:99], v[162:163]
	v_add_u32_e32 v190, 16, v216
	v_and_b32_e32 v191, 63, v190
	v_pk_mul_f32 v[100:101], v[110:111], v[122:123] op_sel_hi:[1,0]
	v_pk_mul_f32 v[106:107], v[106:107], v[122:123] op_sel_hi:[1,0]
	v_pk_mul_f32 v[102:103], v[102:103], v[122:123] op_sel_hi:[1,0]
	v_pk_mul_f32 v[104:105], v[112:113], v[122:123] op_sel_hi:[1,0]
	v_pk_mul_f32 v[114:115], v[142:143], v[100:101]
	v_pk_mul_f32 v[100:101], v[108:109], v[122:123] op_sel_hi:[1,0]
	v_pk_mul_f32 v[110:111], v[138:139], v[106:107]
	v_pk_mul_f32 v[106:107], v[116:117], v[122:123] op_sel_hi:[1,0]
	v_pk_mul_f32 v[108:109], v[134:135], v[102:103]
	v_pk_mul_f32 v[112:113], v[120:121], v[122:123] op_sel_hi:[1,0]
	v_pk_mul_f32 v[102:103], v[118:119], v[122:123] op_sel_hi:[1,0]
	v_cvt_f32_ubyte0_e32 v116, v191
	v_pk_mul_f32 v[104:105], v[144:145], v[104:105]
	v_pk_mul_f32 v[100:101], v[140:141], v[100:101]
	v_pk_mul_f32 v[106:107], v[136:137], v[106:107]
	v_pk_mul_f32 v[102:103], v[132:133], v[102:103]
	v_pk_mul_f32 v[112:113], v[130:131], v[112:113]
	s_and_b64 vcc, exec, s[42:43]
	v_mul_f32_e32 v120, v0, v116
	v_mul_f32_e32 v119, v165, v116
	v_mul_f32_e32 v118, v167, v116
	v_mul_f32_e32 v117, v169, v116
	s_cbranch_vccnz .LBB0_664
	v_ashrrev_i32_e32 v121, 6, v190
	v_cvt_f32_i32_e32 v121, v121
	v_mul_f32_e32 v122, v0, v121
	v_mul_f32_e32 v123, v165, v121
	v_floor_f32_e32 v122, v122
	v_floor_f32_e32 v123, v123
	v_fma_f32 v124, v0, v121, -v122
	v_fma_f32 v125, v165, v121, -v123
	v_sin_f32_e32 v122, v124
	v_cos_f32_e32 v124, v124
	v_sin_f32_e32 v123, v125
	v_cos_f32_e32 v125, v125
	v_mul_f32_e32 v126, v167, v121
	v_floor_f32_e32 v126, v126
	v_mul_f32_e32 v187, v169, v121
	v_fma_f32 v126, v167, v121, -v126
	v_floor_f32_e32 v187, v187
	v_cos_f32_e32 v129, v126
	v_sin_f32_e32 v176, v126
	v_pk_mul_f32 v[126:127], v[122:123], v[110:111]
	v_pk_mul_f32 v[110:111], v[124:125], v[110:111]
	v_fma_f32 v121, v169, v121, -v187
	v_sin_f32_e32 v191, v121
	v_cos_f32_e32 v190, v121
	v_pk_fma_f32 v[124:125], v[124:125], v[114:115], v[126:127] neg_lo:[0,0,1] neg_hi:[0,0,1]
	v_pk_fma_f32 v[110:111], v[122:123], v[114:115], v[110:111]
	v_floor_f32_e32 v114, v120
	v_fma_f32 v115, v0, v116, -v114
	v_sin_f32_e32 v114, v115
	v_cos_f32_e32 v122, v115
	v_floor_f32_e32 v115, v119
	v_mul_f32_e32 v186, v176, v100
	v_mul_f32_e32 v194, v129, v100
	v_mov_b32_e32 v100, v105
	v_fma_f32 v121, v165, v116, -v115
	v_mul_f32_e32 v128, v129, v104
	v_mul_f32_e32 v192, v176, v104
	v_pk_mul_f32 v[104:105], v[190:191], v[100:101]
	v_sin_f32_e32 v115, v121
	v_cos_f32_e32 v123, v121
	v_floor_f32_e32 v121, v118
	v_mov_b32_e32 v129, v104
	v_mov_b32_e32 v187, v105
	v_mov_b32_e32 v104, v191
	v_mov_b32_e32 v105, v190
	v_fma_f32 v121, v167, v116, -v121
	v_floor_f32_e32 v176, v117
	v_pk_mul_f32 v[100:101], v[104:105], v[100:101]
	v_pk_add_f32 v[104:105], v[128:129], v[186:187] neg_lo:[0,1] neg_hi:[0,1]
	v_cos_f32_e32 v129, v121
	v_sin_f32_e32 v121, v121
	v_fma_f32 v176, v169, v116, -v176
	v_sin_f32_e32 v191, v176
	v_cos_f32_e32 v190, v176
	v_mov_b32_e32 v193, v100
	v_mov_b32_e32 v195, v101
	v_pk_add_f32 v[100:101], v[192:193], v[194:195]
	v_mul_f32_e32 v186, v121, v102
	v_mul_f32_e32 v194, v129, v102
	v_mov_b32_e32 v102, v107
	v_mul_f32_e32 v128, v129, v106
	v_mul_f32_e32 v192, v121, v106
	v_pk_mul_f32 v[106:107], v[190:191], v[102:103]
	v_pk_mul_f32 v[126:127], v[114:115], v[112:113]
	v_mov_b32_e32 v129, v106
	v_mov_b32_e32 v187, v107
	v_mov_b32_e32 v106, v191
	v_mov_b32_e32 v107, v190
	v_pk_mul_f32 v[102:103], v[106:107], v[102:103]
	v_pk_mul_f32 v[112:113], v[122:123], v[112:113]
	v_mov_b32_e32 v193, v102
	v_mov_b32_e32 v195, v103
	v_pk_fma_f32 v[122:123], v[122:123], v[108:109], v[126:127] neg_lo:[0,0,1] neg_hi:[0,0,1]
	v_pk_add_f32 v[106:107], v[128:129], v[186:187] neg_lo:[0,1] neg_hi:[0,1]
	v_pk_fma_f32 v[112:113], v[114:115], v[108:109], v[112:113]
	v_pk_add_f32 v[102:103], v[192:193], v[194:195]
	v_mov_b32_e32 v114, v124
	v_mov_b32_e32 v115, v125
	v_mov_b32_e32 v108, v122
	v_mov_b32_e32 v109, v123
.LBB0_664:
	s_movk_i32 s2, 0x4000
	v_add_co_u32_e32 v98, vcc, s2, v98
	v_pk_mul_f32 v[104:105], v[104:105], s[12:13] op_sel_hi:[1,0]
	v_pk_mul_f32 v[114:115], v[114:115], s[12:13] op_sel_hi:[1,0]
	v_pk_mul_f32 v[100:101], v[100:101], s[12:13] op_sel_hi:[1,0]
	v_addc_co_u32_e32 v99, vcc, 0, v99, vcc
	v_pk_mul_f32 v[110:111], v[110:111], s[12:13] op_sel_hi:[1,0]
	v_pk_mul_f32 v[106:107], v[106:107], s[12:13] op_sel_hi:[1,0]
	v_pk_mul_f32 v[108:109], v[108:109], s[12:13] op_sel_hi:[1,0]
	v_pk_mul_f32 v[102:103], v[102:103], s[12:13] op_sel_hi:[1,0]
	v_cvt_pk_bf16_f32 v240, v114, v115
	v_cvt_pk_bf16_f32 v241, v104, v105
	v_mbcnt_lo_u32_b32 v252, -1, 0
	v_mbcnt_hi_u32_b32 v252, -1, v252
	v_bfe_u32 v252, v252, 4, 1
	v_mul_u32_u24_e32 v252, 24, v252
	v_mov_b32_e32 v253, 0
	v_lshl_add_u64 v[248:249], v[98:99], 0, v[252:253]
	v_cvt_pk_bf16_f32 v242, v110, v111
	v_cvt_pk_bf16_f32 v243, v100, v101
	s_nop 1
	v_permlane16_swap_b32_e32 v240, v242
	v_permlane16_swap_b32_e32 v241, v243
	global_store_dwordx4 v[248:249], v[240:243], off
	v_cvt_pk_bf16_f32 v244, v108, v109
	v_cvt_pk_bf16_f32 v245, v106, v107
	v_xor_b32_e32 v121, 32, v189
	v_pk_mul_f32 v[112:113], v[112:113], s[12:13] op_sel_hi:[1,0]
	v_cvt_pk_bf16_f32 v246, v112, v113
	v_cvt_pk_bf16_f32 v247, v102, v103
	s_nop 1
	v_permlane16_swap_b32_e32 v244, v246
	v_permlane16_swap_b32_e32 v245, v247
	global_store_dwordx4 v[248:249], v[244:247], off offset:64
	v_pk_fma_f32 v[96:97], v[96:97], v[174:175], v[160:161] op_sel_hi:[1,0,1]
	v_pk_fma_f32 v[94:95], v[94:95], v[174:175], v[158:159] op_sel_hi:[1,0,1]
	v_pk_fma_f32 v[104:105], v[82:83], v[174:175], v[146:147] op_sel_hi:[1,0,1]
	v_mul_f32_e32 v82, v95, v95
	v_mul_f32_e32 v83, v97, v97
	v_pk_fma_f32 v[92:93], v[92:93], v[174:175], v[156:157] op_sel_hi:[1,0,1]
	v_pk_fma_f32 v[90:91], v[90:91], v[174:175], v[154:155] op_sel_hi:[1,0,1]
	v_fmac_f32_e32 v82, v94, v94
	v_fmac_f32_e32 v83, v96, v96
	v_pk_fma_f32 v[102:103], v[84:85], v[174:175], v[148:149] op_sel_hi:[1,0,1]
	v_add_f32_e32 v82, v82, v83
	v_mul_f32_e32 v83, v91, v91
	v_mul_f32_e32 v84, v93, v93
	v_fmac_f32_e32 v83, v90, v90
	v_fmac_f32_e32 v84, v92, v92
	v_pk_fma_f32 v[88:89], v[88:89], v[174:175], v[152:153] op_sel_hi:[1,0,1]
	v_pk_fma_f32 v[100:101], v[86:87], v[174:175], v[150:151] op_sel_hi:[1,0,1]
	v_add_f32_e32 v83, v83, v84
	v_add_f32_e32 v82, v82, v83
	v_mul_f32_e32 v83, v101, v101
	v_mul_f32_e32 v84, v89, v89
	v_fmac_f32_e32 v83, v100, v100
	v_fmac_f32_e32 v84, v88, v88
	v_add_f32_e32 v83, v83, v84
	v_add_f32_e32 v82, v82, v83
	v_mul_f32_e32 v83, v105, v105
	v_mul_f32_e32 v84, v103, v103
	v_fmac_f32_e32 v83, v104, v104
	v_fmac_f32_e32 v84, v102, v102
	v_add_f32_e32 v83, v83, v84
	v_add_f32_e32 v82, v82, v83
	v_mov_b32_e32 v83, v82
	s_nop 1
	v_permlane16_swap_b32_e32 v82, v83
	v_add_f32_e32 v82, v82, v83
	v_mov_b32_e32 v83, v82
	s_nop 1
	v_permlane32_swap_b32_e32 v82, v83
	v_add_f32_e32 v82, v82, v83
	v_fmamk_f32 v82, v82, 0x3c800000, v223
	v_rsq_f32_e32 v106, v82
	v_mov_b64_e32 v[82:83], v[162:163]
	v_mov_b64_e32 v[84:85], 0
	v_pk_mul_f32 v[90:91], v[90:91], v[106:107] op_sel_hi:[1,0]
	v_pk_mul_f32 v[84:85], v[94:95], v[106:107] op_sel_hi:[1,0]
	v_pk_mul_f32 v[88:89], v[88:89], v[106:107] op_sel_hi:[1,0]
	v_pk_mul_f32 v[86:87], v[96:97], v[106:107] op_sel_hi:[1,0]
	v_pk_mul_f32 v[98:99], v[142:143], v[84:85]
	v_pk_mul_f32 v[84:85], v[92:93], v[106:107] op_sel_hi:[1,0]
	v_pk_mul_f32 v[94:95], v[138:139], v[90:91]
	v_pk_mul_f32 v[92:93], v[100:101], v[106:107] op_sel_hi:[1,0]
	v_pk_mul_f32 v[90:91], v[136:137], v[88:89]
	v_pk_mul_f32 v[96:97], v[104:105], v[106:107] op_sel_hi:[1,0]
	v_pk_mul_f32 v[88:89], v[102:103], v[106:107] op_sel_hi:[1,0]
	v_cvt_f32_ubyte0_e32 v100, v121
	v_pk_mul_f32 v[86:87], v[144:145], v[86:87]
	v_pk_mul_f32 v[84:85], v[140:141], v[84:85]
	v_pk_mul_f32 v[92:93], v[134:135], v[92:93]
	v_pk_mul_f32 v[88:89], v[132:133], v[88:89]
	v_pk_mul_f32 v[96:97], v[130:131], v[96:97]
	s_and_b64 vcc, exec, s[42:43]
	v_mul_f32_e32 v104, v0, v100
	v_mul_f32_e32 v103, v165, v100
	v_mul_f32_e32 v102, v167, v100
	v_mul_f32_e32 v101, v169, v100
	s_cbranch_vccnz .LBB0_666
	v_add_u32_e32 v105, 32, v216
	v_ashrrev_i32_e32 v105, 6, v105
	v_cvt_f32_i32_e32 v105, v105
	v_mul_f32_e32 v106, v0, v105
	v_mul_f32_e32 v107, v165, v105
	v_floor_f32_e32 v106, v106
	v_floor_f32_e32 v107, v107
	v_fma_f32 v108, v0, v105, -v106
	v_fma_f32 v109, v165, v105, -v107
	v_sin_f32_e32 v106, v108
	v_cos_f32_e32 v108, v108
	v_sin_f32_e32 v107, v109
	v_cos_f32_e32 v109, v109
	v_mul_f32_e32 v110, v167, v105
	v_floor_f32_e32 v110, v110
	v_mul_f32_e32 v121, v169, v105
	v_fma_f32 v110, v167, v105, -v110
	v_floor_f32_e32 v121, v121
	v_cos_f32_e32 v113, v110
	v_sin_f32_e32 v115, v110
	v_fma_f32 v105, v169, v105, -v121
	v_pk_mul_f32 v[110:111], v[106:107], v[94:95]
	v_pk_mul_f32 v[94:95], v[108:109], v[94:95]
	v_sin_f32_e32 v123, v105
	v_cos_f32_e32 v122, v105
	v_pk_fma_f32 v[108:109], v[108:109], v[98:99], v[110:111] neg_lo:[0,0,1] neg_hi:[0,0,1]
	v_pk_fma_f32 v[94:95], v[106:107], v[98:99], v[94:95]
	v_floor_f32_e32 v98, v104
	v_fma_f32 v99, v0, v100, -v98
	v_mul_f32_e32 v114, v115, v84
	v_mul_f32_e32 v126, v113, v84
	v_mov_b32_e32 v84, v87
	v_sin_f32_e32 v98, v99
	v_cos_f32_e32 v106, v99
	v_floor_f32_e32 v99, v103
	v_mul_f32_e32 v112, v113, v86
	v_mul_f32_e32 v124, v115, v86
	v_pk_mul_f32 v[86:87], v[122:123], v[84:85]
	v_fma_f32 v105, v165, v100, -v99
	v_mov_b32_e32 v113, v86
	v_mov_b32_e32 v115, v87
	v_mov_b32_e32 v86, v123
	v_mov_b32_e32 v87, v122
	v_sin_f32_e32 v99, v105
	v_cos_f32_e32 v107, v105
	v_floor_f32_e32 v105, v102
	v_pk_mul_f32 v[84:85], v[86:87], v[84:85]
	v_pk_add_f32 v[86:87], v[112:113], v[114:115] neg_lo:[0,1] neg_hi:[0,1]
	v_fma_f32 v105, v167, v100, -v105
	v_floor_f32_e32 v115, v101
	v_cos_f32_e32 v113, v105
	v_sin_f32_e32 v105, v105
	v_fma_f32 v115, v169, v100, -v115
	v_sin_f32_e32 v123, v115
	v_cos_f32_e32 v122, v115
	v_mov_b32_e32 v125, v84
	v_mov_b32_e32 v127, v85
	v_pk_add_f32 v[84:85], v[124:125], v[126:127]
	v_mul_f32_e32 v114, v105, v88
	v_mul_f32_e32 v126, v113, v88
	v_mov_b32_e32 v88, v91
	v_mul_f32_e32 v112, v113, v90
	v_mul_f32_e32 v124, v105, v90
	v_pk_mul_f32 v[90:91], v[122:123], v[88:89]
	v_pk_mul_f32 v[110:111], v[98:99], v[96:97]
	v_mov_b32_e32 v113, v90
	v_mov_b32_e32 v115, v91
	v_mov_b32_e32 v90, v123
	v_mov_b32_e32 v91, v122
	v_pk_mul_f32 v[88:89], v[90:91], v[88:89]
	v_pk_mul_f32 v[96:97], v[106:107], v[96:97]
	v_mov_b32_e32 v125, v88
	v_mov_b32_e32 v127, v89
	v_pk_fma_f32 v[106:107], v[106:107], v[92:93], v[110:111] neg_lo:[0,0,1] neg_hi:[0,0,1]
	v_pk_add_f32 v[90:91], v[112:113], v[114:115] neg_lo:[0,1] neg_hi:[0,1]
	v_pk_fma_f32 v[96:97], v[98:99], v[92:93], v[96:97]
	v_pk_add_f32 v[88:89], v[124:125], v[126:127]
	v_mov_b32_e32 v98, v108
	v_mov_b32_e32 v99, v109
	v_mov_b32_e32 v92, v106
	v_mov_b32_e32 v93, v107
.LBB0_666:
	s_mov_b32 s2, 0x8000
	v_add_co_u32_e32 v82, vcc, s2, v82
	v_pk_mul_f32 v[86:87], v[86:87], s[12:13] op_sel_hi:[1,0]
	v_pk_mul_f32 v[98:99], v[98:99], s[12:13] op_sel_hi:[1,0]
	v_pk_mul_f32 v[84:85], v[84:85], s[12:13] op_sel_hi:[1,0]
	v_addc_co_u32_e32 v83, vcc, 0, v83, vcc
	v_pk_mul_f32 v[94:95], v[94:95], s[12:13] op_sel_hi:[1,0]
	v_pk_mul_f32 v[90:91], v[90:91], s[12:13] op_sel_hi:[1,0]
	v_pk_mul_f32 v[92:93], v[92:93], s[12:13] op_sel_hi:[1,0]
	v_pk_mul_f32 v[88:89], v[88:89], s[12:13] op_sel_hi:[1,0]
	v_cvt_pk_bf16_f32 v240, v98, v99
	v_cvt_pk_bf16_f32 v241, v86, v87
	v_mbcnt_lo_u32_b32 v252, -1, 0
	v_mbcnt_hi_u32_b32 v252, -1, v252
	v_bfe_u32 v252, v252, 4, 1
	v_mul_u32_u24_e32 v252, 24, v252
	v_mov_b32_e32 v253, 0
	v_lshl_add_u64 v[248:249], v[82:83], 0, v[252:253]
	v_cvt_pk_bf16_f32 v242, v94, v95
	v_cvt_pk_bf16_f32 v243, v84, v85
	s_nop 1
	v_permlane16_swap_b32_e32 v240, v242
	v_permlane16_swap_b32_e32 v241, v243
	global_store_dwordx4 v[248:249], v[240:243], off
	v_cvt_pk_bf16_f32 v244, v92, v93
	v_cvt_pk_bf16_f32 v245, v90, v91
	v_pk_fma_f32 v[80:81], v[80:81], v[172:173], v[160:161] op_sel_hi:[1,0,1]
	v_pk_fma_f32 v[78:79], v[78:79], v[172:173], v[158:159] op_sel_hi:[1,0,1]
	v_pk_mul_f32 v[96:97], v[96:97], s[12:13] op_sel_hi:[1,0]
	v_cvt_pk_bf16_f32 v246, v96, v97
	v_cvt_pk_bf16_f32 v247, v88, v89
	v_pk_fma_f32 v[88:89], v[66:67], v[172:173], v[146:147] op_sel_hi:[1,0,1]
	v_mul_f32_e32 v66, v79, v79
	v_mul_f32_e32 v67, v81, v81
	v_pk_fma_f32 v[76:77], v[76:77], v[172:173], v[156:157] op_sel_hi:[1,0,1]
	v_pk_fma_f32 v[74:75], v[74:75], v[172:173], v[154:155] op_sel_hi:[1,0,1]
	v_fmac_f32_e32 v66, v78, v78
	v_fmac_f32_e32 v67, v80, v80
	v_pk_fma_f32 v[86:87], v[68:69], v[172:173], v[148:149] op_sel_hi:[1,0,1]
	v_add_f32_e32 v66, v66, v67
	v_mul_f32_e32 v67, v75, v75
	v_mul_f32_e32 v68, v77, v77
	v_fmac_f32_e32 v67, v74, v74
	v_fmac_f32_e32 v68, v76, v76
	s_nop 1
	v_permlane16_swap_b32_e32 v244, v246
	v_permlane16_swap_b32_e32 v245, v247
	global_store_dwordx4 v[248:249], v[244:247], off offset:64
	v_pk_fma_f32 v[84:85], v[72:73], v[172:173], v[152:153] op_sel_hi:[1,0,1]
	v_pk_fma_f32 v[70:71], v[70:71], v[172:173], v[150:151] op_sel_hi:[1,0,1]
	v_add_f32_e32 v67, v67, v68
	v_add_f32_e32 v66, v66, v67
	v_mul_f32_e32 v67, v71, v71
	v_mul_f32_e32 v68, v85, v85
	v_fmac_f32_e32 v67, v70, v70
	v_fmac_f32_e32 v68, v84, v84
	v_add_f32_e32 v67, v67, v68
	v_add_f32_e32 v66, v66, v67
	v_mul_f32_e32 v67, v89, v89
	v_mul_f32_e32 v68, v87, v87
	v_fmac_f32_e32 v67, v88, v88
	v_fmac_f32_e32 v68, v86, v86
	v_add_f32_e32 v67, v67, v68
	v_add_f32_e32 v66, v66, v67
	v_mov_b32_e32 v67, v66
	s_nop 1
	v_permlane16_swap_b32_e32 v66, v67
	v_add_f32_e32 v66, v66, v67
	v_mov_b32_e32 v67, v66
	s_nop 1
	v_permlane32_swap_b32_e32 v66, v67
	v_add_f32_e32 v66, v66, v67
	v_fmamk_f32 v66, v66, 0x3c800000, v223
	v_rsq_f32_e32 v90, v66
	v_mov_b64_e32 v[66:67], v[162:163]
	v_mov_b64_e32 v[68:69], 0
	v_add_u32_e32 v105, 48, v216
	v_and_b32_e32 v106, 63, v105
	v_pk_mul_f32 v[68:69], v[78:79], v[90:91] op_sel_hi:[1,0]
	v_pk_mul_f32 v[74:75], v[74:75], v[90:91] op_sel_hi:[1,0]
	v_pk_mul_f32 v[70:71], v[70:71], v[90:91] op_sel_hi:[1,0]
	v_pk_mul_f32 v[72:73], v[80:81], v[90:91] op_sel_hi:[1,0]
	v_pk_mul_f32 v[82:83], v[142:143], v[68:69]
	v_pk_mul_f32 v[68:69], v[76:77], v[90:91] op_sel_hi:[1,0]
	v_pk_mul_f32 v[78:79], v[138:139], v[74:75]
	v_pk_mul_f32 v[74:75], v[84:85], v[90:91] op_sel_hi:[1,0]
	v_pk_mul_f32 v[76:77], v[134:135], v[70:71]
	v_pk_mul_f32 v[80:81], v[88:89], v[90:91] op_sel_hi:[1,0]
	v_pk_mul_f32 v[70:71], v[86:87], v[90:91] op_sel_hi:[1,0]
	v_cvt_f32_ubyte0_e32 v84, v106
	v_pk_mul_f32 v[72:73], v[144:145], v[72:73]
	v_pk_mul_f32 v[68:69], v[140:141], v[68:69]
	v_pk_mul_f32 v[74:75], v[136:137], v[74:75]
	v_pk_mul_f32 v[70:71], v[132:133], v[70:71]
	v_pk_mul_f32 v[80:81], v[130:131], v[80:81]
	s_and_b64 vcc, exec, s[42:43]
	v_mul_f32_e32 v88, v0, v84
	v_mul_f32_e32 v87, v165, v84
	v_mul_f32_e32 v86, v167, v84
	v_mul_f32_e32 v85, v169, v84
	s_cbranch_vccnz .LBB0_668
	v_ashrrev_i32_e32 v89, 6, v105
	v_cvt_f32_i32_e32 v89, v89
	v_mul_f32_e32 v90, v0, v89
	v_mul_f32_e32 v91, v165, v89
	v_floor_f32_e32 v90, v90
	v_floor_f32_e32 v91, v91
	v_fma_f32 v92, v0, v89, -v90
	v_fma_f32 v93, v165, v89, -v91
	v_sin_f32_e32 v90, v92
	v_cos_f32_e32 v92, v92
	v_sin_f32_e32 v91, v93
	v_cos_f32_e32 v93, v93
	v_mul_f32_e32 v94, v167, v89
	v_floor_f32_e32 v94, v94
	v_mul_f32_e32 v105, v169, v89
	v_fma_f32 v94, v167, v89, -v94
	v_floor_f32_e32 v105, v105
	v_cos_f32_e32 v97, v94
	v_sin_f32_e32 v99, v94
	v_fma_f32 v89, v169, v89, -v105
	v_pk_mul_f32 v[94:95], v[90:91], v[78:79]
	v_pk_mul_f32 v[78:79], v[92:93], v[78:79]
	v_sin_f32_e32 v107, v89
	v_cos_f32_e32 v106, v89
	v_pk_fma_f32 v[92:93], v[92:93], v[82:83], v[94:95] neg_lo:[0,0,1] neg_hi:[0,0,1]
	v_pk_fma_f32 v[78:79], v[90:91], v[82:83], v[78:79]
	v_floor_f32_e32 v82, v88
	v_fma_f32 v83, v0, v84, -v82
	v_mul_f32_e32 v98, v99, v68
	v_mul_f32_e32 v110, v97, v68
	v_mov_b32_e32 v68, v73
	v_sin_f32_e32 v82, v83
	v_cos_f32_e32 v90, v83
	v_floor_f32_e32 v83, v87
	v_mul_f32_e32 v96, v97, v72
	v_mul_f32_e32 v108, v99, v72
	v_pk_mul_f32 v[72:73], v[106:107], v[68:69]
	v_fma_f32 v89, v165, v84, -v83
	v_mov_b32_e32 v97, v72
	v_mov_b32_e32 v99, v73
	v_mov_b32_e32 v72, v107
	v_mov_b32_e32 v73, v106
	v_sin_f32_e32 v83, v89
	v_cos_f32_e32 v91, v89
	v_floor_f32_e32 v89, v86
	v_pk_mul_f32 v[68:69], v[72:73], v[68:69]
	v_pk_add_f32 v[72:73], v[96:97], v[98:99] neg_lo:[0,1] neg_hi:[0,1]
	v_fma_f32 v89, v167, v84, -v89
	v_floor_f32_e32 v99, v85
	v_cos_f32_e32 v97, v89
	v_sin_f32_e32 v89, v89
	v_fma_f32 v99, v169, v84, -v99
	v_sin_f32_e32 v107, v99
	v_cos_f32_e32 v106, v99
	v_mov_b32_e32 v109, v68
	v_mov_b32_e32 v111, v69
	v_pk_add_f32 v[68:69], v[108:109], v[110:111]
	v_mul_f32_e32 v98, v89, v70
	v_mul_f32_e32 v110, v97, v70
	v_mov_b32_e32 v70, v75
	v_mul_f32_e32 v96, v97, v74
	v_mul_f32_e32 v108, v89, v74
	v_pk_mul_f32 v[74:75], v[106:107], v[70:71]
	v_pk_mul_f32 v[94:95], v[82:83], v[80:81]
	v_mov_b32_e32 v97, v74
	v_mov_b32_e32 v99, v75
	v_mov_b32_e32 v74, v107
	v_mov_b32_e32 v75, v106
	v_pk_mul_f32 v[70:71], v[74:75], v[70:71]
	v_pk_mul_f32 v[80:81], v[90:91], v[80:81]
	v_mov_b32_e32 v109, v70
	v_mov_b32_e32 v111, v71
	v_pk_fma_f32 v[90:91], v[90:91], v[76:77], v[94:95] neg_lo:[0,0,1] neg_hi:[0,0,1]
	v_pk_add_f32 v[74:75], v[96:97], v[98:99] neg_lo:[0,1] neg_hi:[0,1]
	v_pk_fma_f32 v[80:81], v[82:83], v[76:77], v[80:81]
	v_pk_add_f32 v[70:71], v[108:109], v[110:111]
	v_mov_b32_e32 v82, v92
	v_mov_b32_e32 v83, v93
	v_mov_b32_e32 v76, v90
	v_mov_b32_e32 v77, v91
.LBB0_668:
	s_mov_b32 s2, 0xc000
	v_add_co_u32_e32 v66, vcc, s2, v66
	v_pk_mul_f32 v[72:73], v[72:73], s[12:13] op_sel_hi:[1,0]
	v_pk_mul_f32 v[82:83], v[82:83], s[12:13] op_sel_hi:[1,0]
	v_pk_mul_f32 v[68:69], v[68:69], s[12:13] op_sel_hi:[1,0]
	v_addc_co_u32_e32 v67, vcc, 0, v67, vcc
	v_pk_mul_f32 v[78:79], v[78:79], s[12:13] op_sel_hi:[1,0]
	v_pk_mul_f32 v[74:75], v[74:75], s[12:13] op_sel_hi:[1,0]
	v_pk_mul_f32 v[76:77], v[76:77], s[12:13] op_sel_hi:[1,0]
	v_cvt_pk_bf16_f32 v240, v82, v83
	v_cvt_pk_bf16_f32 v241, v72, v73
	v_mbcnt_lo_u32_b32 v252, -1, 0
	v_mbcnt_hi_u32_b32 v252, -1, v252
	v_bfe_u32 v252, v252, 4, 1
	v_mul_u32_u24_e32 v252, 24, v252
	v_mov_b32_e32 v253, 0
	v_lshl_add_u64 v[248:249], v[66:67], 0, v[252:253]
	v_cvt_pk_bf16_f32 v242, v78, v79
	v_cvt_pk_bf16_f32 v243, v68, v69
	s_nop 1
	v_permlane16_swap_b32_e32 v240, v242
	v_permlane16_swap_b32_e32 v241, v243
	global_store_dwordx4 v[248:249], v[240:243], off
	v_cvt_pk_bf16_f32 v244, v76, v77
	v_cvt_pk_bf16_f32 v245, v74, v75
	v_pk_mul_f32 v[70:71], v[70:71], s[12:13] op_sel_hi:[1,0]
	v_pk_mul_f32 v[80:81], v[80:81], s[12:13] op_sel_hi:[1,0]
	v_cvt_pk_bf16_f32 v246, v80, v81
	v_cvt_pk_bf16_f32 v247, v70, v71
	s_nop 1
	v_permlane16_swap_b32_e32 v244, v246
	v_permlane16_swap_b32_e32 v245, v247
	global_store_dwordx4 v[248:249], v[244:247], off offset:64
	v_pk_fma_f32 v[64:65], v[64:65], v[170:171], v[160:161] op_sel_hi:[1,0,1]
	v_pk_fma_f32 v[62:63], v[62:63], v[170:171], v[158:159] op_sel_hi:[1,0,1]
	v_pk_fma_f32 v[72:73], v[50:51], v[170:171], v[146:147] op_sel_hi:[1,0,1]
	v_mul_f32_e32 v50, v63, v63
	v_mul_f32_e32 v51, v65, v65
	v_pk_fma_f32 v[60:61], v[60:61], v[170:171], v[156:157] op_sel_hi:[1,0,1]
	v_pk_fma_f32 v[58:59], v[58:59], v[170:171], v[154:155] op_sel_hi:[1,0,1]
	v_fmac_f32_e32 v50, v62, v62
	v_fmac_f32_e32 v51, v64, v64
	v_pk_fma_f32 v[70:71], v[52:53], v[170:171], v[148:149] op_sel_hi:[1,0,1]
	v_add_f32_e32 v50, v50, v51
	v_mul_f32_e32 v51, v59, v59
	v_mul_f32_e32 v52, v61, v61
	v_fmac_f32_e32 v51, v58, v58
	v_fmac_f32_e32 v52, v60, v60
	v_pk_fma_f32 v[56:57], v[56:57], v[170:171], v[152:153] op_sel_hi:[1,0,1]
	v_pk_fma_f32 v[68:69], v[54:55], v[170:171], v[150:151] op_sel_hi:[1,0,1]
	v_add_f32_e32 v51, v51, v52
	v_add_f32_e32 v50, v50, v51
	v_mul_f32_e32 v51, v69, v69
	v_mul_f32_e32 v52, v57, v57
	v_fmac_f32_e32 v51, v68, v68
	v_fmac_f32_e32 v52, v56, v56
	v_add_f32_e32 v51, v51, v52
	v_add_f32_e32 v50, v51, v50
	v_mul_f32_e32 v51, v73, v73
	v_mul_f32_e32 v52, v71, v71
	v_fmac_f32_e32 v51, v72, v72
	v_fmac_f32_e32 v52, v70, v70
	v_add_f32_e32 v51, v51, v52
	v_add_f32_e32 v50, v51, v50
	v_mov_b32_e32 v51, v50
	s_nop 1
	v_permlane16_swap_b32_e32 v50, v51
	v_add_f32_e32 v50, v50, v51
	v_mov_b32_e32 v51, v50
	s_nop 1
	v_permlane32_swap_b32_e32 v50, v51
	v_add_f32_e32 v50, v50, v51
	v_fmamk_f32 v50, v50, 0x3c800000, v223
	v_rsq_f32_e32 v74, v50
	v_mov_b64_e32 v[50:51], v[162:163]
	v_mov_b64_e32 v[52:53], 0
	v_pk_mul_f32 v[58:59], v[58:59], v[74:75] op_sel_hi:[1,0]
	v_pk_mul_f32 v[52:53], v[62:63], v[74:75] op_sel_hi:[1,0]
	v_pk_mul_f32 v[56:57], v[56:57], v[74:75] op_sel_hi:[1,0]
	v_pk_mul_f32 v[54:55], v[64:65], v[74:75] op_sel_hi:[1,0]
	v_pk_mul_f32 v[66:67], v[142:143], v[52:53]
	v_pk_mul_f32 v[52:53], v[60:61], v[74:75] op_sel_hi:[1,0]
	v_pk_mul_f32 v[62:63], v[138:139], v[58:59]
	v_pk_mul_f32 v[60:61], v[68:69], v[74:75] op_sel_hi:[1,0]
	v_pk_mul_f32 v[58:59], v[136:137], v[56:57]
	v_pk_mul_f32 v[64:65], v[72:73], v[74:75] op_sel_hi:[1,0]
	v_pk_mul_f32 v[56:57], v[70:71], v[74:75] op_sel_hi:[1,0]
	v_pk_mul_f32 v[54:55], v[144:145], v[54:55]
	v_pk_mul_f32 v[52:53], v[140:141], v[52:53]
	v_pk_mul_f32 v[60:61], v[134:135], v[60:61]
	v_pk_mul_f32 v[56:57], v[132:133], v[56:57]
	s_and_b64 vcc, exec, s[42:43]
	v_pk_mul_f32 v[64:65], v[130:131], v[64:65]
	s_cbranch_vccnz .LBB0_670
	v_add_u32_e32 v68, 0x80, v216
	v_ashrrev_i32_e32 v68, 6, v68
	v_cvt_f32_i32_e32 v75, v68
	v_mul_f32_e32 v68, v0, v75
	v_mul_f32_e32 v69, v165, v75
	v_mul_f32_e32 v72, v167, v75
	v_floor_f32_e32 v68, v68
	v_floor_f32_e32 v69, v69
	v_floor_f32_e32 v72, v72
	v_mul_f32_e32 v78, v169, v75
	v_fma_f32 v70, v0, v75, -v68
	v_fma_f32 v71, v165, v75, -v69
	v_fma_f32 v72, v167, v75, -v72
	v_floor_f32_e32 v78, v78
	v_sin_f32_e32 v68, v70
	v_sin_f32_e32 v69, v71
	v_cos_f32_e32 v77, v72
	v_sin_f32_e32 v80, v72
	v_fma_f32 v75, v169, v75, -v78
	v_cos_f32_e32 v70, v70
	v_cos_f32_e32 v71, v71
	v_sin_f32_e32 v79, v75
	v_cos_f32_e32 v78, v75
	v_pk_mul_f32 v[72:73], v[68:69], v[62:63]
	v_mul_f32_e32 v76, v80, v52
	v_mul_f32_e32 v82, v77, v52
	v_mov_b32_e32 v52, v55
	v_pk_mul_f32 v[62:63], v[70:71], v[62:63]
	v_mul_f32_e32 v74, v77, v54
	v_mul_f32_e32 v80, v80, v54
	v_pk_mul_f32 v[54:55], v[78:79], v[52:53]
	v_pk_fma_f32 v[70:71], v[70:71], v[66:67], v[72:73] neg_lo:[0,0,1] neg_hi:[0,0,1]
	v_floor_f32_e32 v72, v175
	v_mov_b32_e32 v75, v54
	v_mov_b32_e32 v77, v55
	v_mov_b32_e32 v54, v79
	v_mov_b32_e32 v55, v78
	v_pk_fma_f32 v[62:63], v[68:69], v[66:67], v[62:63]
	v_floor_f32_e32 v66, v173
	v_fma_f32 v72, v167, v171, -v72
	v_floor_f32_e32 v78, v188
	v_pk_mul_f32 v[52:53], v[54:55], v[52:53]
	v_pk_add_f32 v[54:55], v[74:75], v[76:77] neg_lo:[0,1] neg_hi:[0,1]
	v_fma_f32 v67, v0, v171, -v66
	v_cos_f32_e32 v75, v72
	v_sin_f32_e32 v77, v72
	v_fma_f32 v78, v169, v171, -v78
	v_sin_f32_e32 v66, v67
	v_cos_f32_e32 v68, v67
	v_floor_f32_e32 v67, v177
	v_sin_f32_e32 v79, v78
	v_cos_f32_e32 v78, v78
	v_fma_f32 v69, v165, v171, -v67
	v_mov_b32_e32 v81, v52
	v_mov_b32_e32 v83, v53
	v_sin_f32_e32 v67, v69
	v_pk_add_f32 v[52:53], v[80:81], v[82:83]
	v_cos_f32_e32 v69, v69
	v_mul_f32_e32 v76, v77, v56
	v_mul_f32_e32 v82, v75, v56
	v_mov_b32_e32 v56, v59
	v_mul_f32_e32 v74, v75, v58
	v_mul_f32_e32 v80, v77, v58
	v_pk_mul_f32 v[58:59], v[78:79], v[56:57]
	v_pk_mul_f32 v[72:73], v[66:67], v[64:65]
	v_mov_b32_e32 v75, v58
	v_mov_b32_e32 v77, v59
	v_mov_b32_e32 v58, v79
	v_mov_b32_e32 v59, v78
	v_pk_mul_f32 v[56:57], v[58:59], v[56:57]
	v_pk_mul_f32 v[64:65], v[68:69], v[64:65]
	v_mov_b32_e32 v81, v56
	v_mov_b32_e32 v83, v57
	v_pk_fma_f32 v[68:69], v[68:69], v[60:61], v[72:73] neg_lo:[0,0,1] neg_hi:[0,0,1]
	v_pk_add_f32 v[58:59], v[74:75], v[76:77] neg_lo:[0,1] neg_hi:[0,1]
	v_pk_fma_f32 v[64:65], v[66:67], v[60:61], v[64:65]
	v_pk_add_f32 v[56:57], v[80:81], v[82:83]
	v_mov_b32_e32 v66, v70
	v_mov_b32_e32 v67, v71
	v_mov_b32_e32 v60, v68
	v_mov_b32_e32 v61, v69
.LBB0_670:
	s_mov_b32 s2, 0x20000
	v_add_co_u32_e32 v50, vcc, s2, v50
	v_pk_mul_f32 v[54:55], v[54:55], s[12:13] op_sel_hi:[1,0]
	v_pk_mul_f32 v[66:67], v[66:67], s[12:13] op_sel_hi:[1,0]
	v_pk_mul_f32 v[52:53], v[52:53], s[12:13] op_sel_hi:[1,0]
	v_addc_co_u32_e32 v51, vcc, 0, v51, vcc
	v_pk_mul_f32 v[62:63], v[62:63], s[12:13] op_sel_hi:[1,0]
	v_pk_mul_f32 v[58:59], v[58:59], s[12:13] op_sel_hi:[1,0]
	v_pk_mul_f32 v[60:61], v[60:61], s[12:13] op_sel_hi:[1,0]
	v_pk_mul_f32 v[56:57], v[56:57], s[12:13] op_sel_hi:[1,0]
	v_cvt_pk_bf16_f32 v240, v66, v67
	v_cvt_pk_bf16_f32 v241, v54, v55
	v_mbcnt_lo_u32_b32 v252, -1, 0
	v_mbcnt_hi_u32_b32 v252, -1, v252
	v_bfe_u32 v252, v252, 4, 1
	v_mul_u32_u24_e32 v252, 24, v252
	v_mov_b32_e32 v253, 0
	v_lshl_add_u64 v[248:249], v[50:51], 0, v[252:253]
	v_cvt_pk_bf16_f32 v242, v62, v63
	v_cvt_pk_bf16_f32 v243, v52, v53
	s_nop 1
	v_permlane16_swap_b32_e32 v240, v242
	v_permlane16_swap_b32_e32 v241, v243
	global_store_dwordx4 v[248:249], v[240:243], off
	v_cvt_pk_bf16_f32 v244, v60, v61
	v_cvt_pk_bf16_f32 v245, v58, v59
	v_pk_fma_f32 v[48:49], v[48:49], v[168:169], v[160:161] op_sel_hi:[1,0,1]
	v_pk_fma_f32 v[46:47], v[46:47], v[168:169], v[158:159] op_sel_hi:[1,0,1]
	v_pk_mul_f32 v[64:65], v[64:65], s[12:13] op_sel_hi:[1,0]
	v_cvt_pk_bf16_f32 v246, v64, v65
	v_cvt_pk_bf16_f32 v247, v56, v57
	v_pk_fma_f32 v[56:57], v[34:35], v[168:169], v[146:147] op_sel_hi:[1,0,1]
	v_mul_f32_e32 v34, v47, v47
	v_mul_f32_e32 v35, v49, v49
	v_pk_fma_f32 v[44:45], v[44:45], v[168:169], v[156:157] op_sel_hi:[1,0,1]
	v_pk_fma_f32 v[42:43], v[42:43], v[168:169], v[154:155] op_sel_hi:[1,0,1]
	v_fmac_f32_e32 v34, v46, v46
	v_fmac_f32_e32 v35, v48, v48
	v_pk_fma_f32 v[54:55], v[36:37], v[168:169], v[148:149] op_sel_hi:[1,0,1]
	v_add_f32_e32 v34, v34, v35
	v_mul_f32_e32 v35, v43, v43
	v_mul_f32_e32 v36, v45, v45
	v_fmac_f32_e32 v35, v42, v42
	v_fmac_f32_e32 v36, v44, v44
	s_nop 1
	v_permlane16_swap_b32_e32 v244, v246
	v_permlane16_swap_b32_e32 v245, v247
	global_store_dwordx4 v[248:249], v[244:247], off offset:64
	v_pk_fma_f32 v[52:53], v[40:41], v[168:169], v[152:153] op_sel_hi:[1,0,1]
	v_pk_fma_f32 v[38:39], v[38:39], v[168:169], v[150:151] op_sel_hi:[1,0,1]
	v_add_f32_e32 v35, v35, v36
	v_add_f32_e32 v34, v34, v35
	v_mul_f32_e32 v35, v39, v39
	v_mul_f32_e32 v36, v53, v53
	v_fmac_f32_e32 v35, v38, v38
	v_fmac_f32_e32 v36, v52, v52
	v_add_f32_e32 v35, v35, v36
	v_add_f32_e32 v34, v35, v34
	v_mul_f32_e32 v35, v57, v57
	v_mul_f32_e32 v36, v55, v55
	v_fmac_f32_e32 v35, v56, v56
	v_fmac_f32_e32 v36, v54, v54
	v_add_f32_e32 v35, v35, v36
	v_add_f32_e32 v34, v35, v34
	v_mov_b32_e32 v35, v34
	s_nop 1
	v_permlane16_swap_b32_e32 v34, v35
	v_add_f32_e32 v34, v34, v35
	v_mov_b32_e32 v35, v34
	s_nop 1
	v_permlane32_swap_b32_e32 v34, v35
	v_add_f32_e32 v34, v34, v35
	v_fmamk_f32 v34, v34, 0x3c800000, v223
	v_rsq_f32_e32 v58, v34
	v_mov_b64_e32 v[36:37], 0
	v_mov_b64_e32 v[34:35], v[162:163]
	v_pk_mul_f32 v[42:43], v[42:43], v[58:59] op_sel_hi:[1,0]
	v_pk_mul_f32 v[36:37], v[46:47], v[58:59] op_sel_hi:[1,0]
	v_pk_mul_f32 v[38:39], v[38:39], v[58:59] op_sel_hi:[1,0]
	v_pk_mul_f32 v[40:41], v[48:49], v[58:59] op_sel_hi:[1,0]
	v_pk_mul_f32 v[50:51], v[142:143], v[36:37]
	v_pk_mul_f32 v[36:37], v[44:45], v[58:59] op_sel_hi:[1,0]
	v_pk_mul_f32 v[46:47], v[138:139], v[42:43]
	v_pk_mul_f32 v[42:43], v[52:53], v[58:59] op_sel_hi:[1,0]
	v_pk_mul_f32 v[44:45], v[134:135], v[38:39]
	v_pk_mul_f32 v[48:49], v[56:57], v[58:59] op_sel_hi:[1,0]
	v_pk_mul_f32 v[38:39], v[54:55], v[58:59] op_sel_hi:[1,0]
	v_pk_mul_f32 v[40:41], v[144:145], v[40:41]
	v_pk_mul_f32 v[36:37], v[140:141], v[36:37]
	v_pk_mul_f32 v[42:43], v[136:137], v[42:43]
	v_pk_mul_f32 v[38:39], v[132:133], v[38:39]
	s_and_b64 vcc, exec, s[42:43]
	v_pk_mul_f32 v[48:49], v[130:131], v[48:49]
	s_cbranch_vccnz .LBB0_672
	v_add_u32_e32 v52, 0x90, v216
	v_ashrrev_i32_e32 v52, 6, v52
	v_cvt_f32_i32_e32 v59, v52
	v_mul_f32_e32 v52, v0, v59
	v_mul_f32_e32 v53, v165, v59
	v_mul_f32_e32 v56, v167, v59
	v_floor_f32_e32 v52, v52
	v_floor_f32_e32 v53, v53
	v_floor_f32_e32 v56, v56
	v_mul_f32_e32 v62, v169, v59
	v_fma_f32 v54, v0, v59, -v52
	v_fma_f32 v55, v165, v59, -v53
	v_fma_f32 v56, v167, v59, -v56
	v_floor_f32_e32 v62, v62
	v_sin_f32_e32 v52, v54
	v_sin_f32_e32 v53, v55
	v_cos_f32_e32 v61, v56
	v_sin_f32_e32 v64, v56
	v_fma_f32 v59, v169, v59, -v62
	v_cos_f32_e32 v54, v54
	v_cos_f32_e32 v55, v55
	v_sin_f32_e32 v63, v59
	v_cos_f32_e32 v62, v59
	v_pk_mul_f32 v[56:57], v[52:53], v[46:47]
	v_mul_f32_e32 v60, v64, v36
	v_mul_f32_e32 v66, v61, v36
	v_mov_b32_e32 v36, v41
	v_pk_mul_f32 v[46:47], v[54:55], v[46:47]
	v_mul_f32_e32 v58, v61, v40
	v_mul_f32_e32 v64, v64, v40
	v_pk_mul_f32 v[40:41], v[62:63], v[36:37]
	v_pk_fma_f32 v[54:55], v[54:55], v[50:51], v[56:57] neg_lo:[0,0,1] neg_hi:[0,0,1]
	v_floor_f32_e32 v56, v118
	v_mov_b32_e32 v59, v40
	v_mov_b32_e32 v61, v41
	v_mov_b32_e32 v40, v63
	v_mov_b32_e32 v41, v62
	v_pk_fma_f32 v[46:47], v[52:53], v[50:51], v[46:47]
	v_floor_f32_e32 v50, v120
	v_fma_f32 v56, v167, v116, -v56
	v_floor_f32_e32 v62, v117
	v_pk_mul_f32 v[36:37], v[40:41], v[36:37]
	v_pk_add_f32 v[40:41], v[58:59], v[60:61] neg_lo:[0,1] neg_hi:[0,1]
	v_fma_f32 v51, v0, v116, -v50
	v_cos_f32_e32 v59, v56
	v_sin_f32_e32 v61, v56
	v_fma_f32 v62, v169, v116, -v62
	v_sin_f32_e32 v50, v51
	v_cos_f32_e32 v52, v51
	v_floor_f32_e32 v51, v119
	v_sin_f32_e32 v63, v62
	v_cos_f32_e32 v62, v62
	v_fma_f32 v53, v165, v116, -v51
	v_mov_b32_e32 v65, v36
	v_mov_b32_e32 v67, v37
	v_sin_f32_e32 v51, v53
	v_pk_add_f32 v[36:37], v[64:65], v[66:67]
	v_cos_f32_e32 v53, v53
	v_mul_f32_e32 v60, v61, v38
	v_mul_f32_e32 v66, v59, v38
	v_mov_b32_e32 v38, v43
	v_mul_f32_e32 v58, v59, v42
	v_mul_f32_e32 v64, v61, v42
	v_pk_mul_f32 v[42:43], v[62:63], v[38:39]
	v_pk_mul_f32 v[56:57], v[50:51], v[48:49]
	v_mov_b32_e32 v59, v42
	v_mov_b32_e32 v61, v43
	v_mov_b32_e32 v42, v63
	v_mov_b32_e32 v43, v62
	v_pk_mul_f32 v[38:39], v[42:43], v[38:39]
	v_pk_mul_f32 v[48:49], v[52:53], v[48:49]
	v_mov_b32_e32 v65, v38
	v_mov_b32_e32 v67, v39
	v_pk_fma_f32 v[52:53], v[52:53], v[44:45], v[56:57] neg_lo:[0,0,1] neg_hi:[0,0,1]
	v_pk_add_f32 v[42:43], v[58:59], v[60:61] neg_lo:[0,1] neg_hi:[0,1]
	v_pk_fma_f32 v[48:49], v[50:51], v[44:45], v[48:49]
	v_pk_add_f32 v[38:39], v[64:65], v[66:67]
	v_mov_b32_e32 v50, v54
	v_mov_b32_e32 v51, v55
	v_mov_b32_e32 v44, v52
	v_mov_b32_e32 v45, v53
.LBB0_672:
	s_mov_b32 s2, 0x24000
	v_add_co_u32_e32 v34, vcc, s2, v34
	v_pk_mul_f32 v[40:41], v[40:41], s[12:13] op_sel_hi:[1,0]
	v_pk_mul_f32 v[50:51], v[50:51], s[12:13] op_sel_hi:[1,0]
	v_pk_mul_f32 v[36:37], v[36:37], s[12:13] op_sel_hi:[1,0]
	v_addc_co_u32_e32 v35, vcc, 0, v35, vcc
	v_pk_mul_f32 v[46:47], v[46:47], s[12:13] op_sel_hi:[1,0]
	v_pk_mul_f32 v[42:43], v[42:43], s[12:13] op_sel_hi:[1,0]
	v_pk_mul_f32 v[44:45], v[44:45], s[12:13] op_sel_hi:[1,0]
	v_cvt_pk_bf16_f32 v240, v50, v51
	v_cvt_pk_bf16_f32 v241, v40, v41
	v_mbcnt_lo_u32_b32 v252, -1, 0
	v_mbcnt_hi_u32_b32 v252, -1, v252
	v_bfe_u32 v252, v252, 4, 1
	v_mul_u32_u24_e32 v252, 24, v252
	v_mov_b32_e32 v253, 0
	v_lshl_add_u64 v[248:249], v[34:35], 0, v[252:253]
	v_cvt_pk_bf16_f32 v242, v46, v47
	v_cvt_pk_bf16_f32 v243, v36, v37
	s_nop 1
	v_permlane16_swap_b32_e32 v240, v242
	v_permlane16_swap_b32_e32 v241, v243
	global_store_dwordx4 v[248:249], v[240:243], off
	v_cvt_pk_bf16_f32 v244, v44, v45
	v_cvt_pk_bf16_f32 v245, v42, v43
	v_pk_mul_f32 v[38:39], v[38:39], s[12:13] op_sel_hi:[1,0]
	v_pk_mul_f32 v[48:49], v[48:49], s[12:13] op_sel_hi:[1,0]
	v_cvt_pk_bf16_f32 v246, v48, v49
	v_cvt_pk_bf16_f32 v247, v38, v39
	s_nop 1
	v_permlane16_swap_b32_e32 v244, v246
	v_permlane16_swap_b32_e32 v245, v247
	global_store_dwordx4 v[248:249], v[244:247], off offset:64
	v_pk_fma_f32 v[32:33], v[32:33], v[166:167], v[160:161] op_sel_hi:[1,0,1]
	v_pk_fma_f32 v[30:31], v[30:31], v[166:167], v[158:159] op_sel_hi:[1,0,1]
	v_pk_fma_f32 v[40:41], v[18:19], v[166:167], v[146:147] op_sel_hi:[1,0,1]
	v_mul_f32_e32 v18, v31, v31
	v_mul_f32_e32 v19, v33, v33
	v_pk_fma_f32 v[28:29], v[28:29], v[166:167], v[156:157] op_sel_hi:[1,0,1]
	v_pk_fma_f32 v[26:27], v[26:27], v[166:167], v[154:155] op_sel_hi:[1,0,1]
	v_fmac_f32_e32 v18, v30, v30
	v_fmac_f32_e32 v19, v32, v32
	v_pk_fma_f32 v[38:39], v[20:21], v[166:167], v[148:149] op_sel_hi:[1,0,1]
	v_add_f32_e32 v18, v18, v19
	v_mul_f32_e32 v19, v27, v27
	v_mul_f32_e32 v20, v29, v29
	v_fmac_f32_e32 v19, v26, v26
	v_fmac_f32_e32 v20, v28, v28
	v_pk_fma_f32 v[24:25], v[24:25], v[166:167], v[152:153] op_sel_hi:[1,0,1]
	v_pk_fma_f32 v[36:37], v[22:23], v[166:167], v[150:151] op_sel_hi:[1,0,1]
	v_add_f32_e32 v19, v19, v20
	v_add_f32_e32 v18, v18, v19
	v_mul_f32_e32 v19, v37, v37
	v_mul_f32_e32 v20, v25, v25
	v_fmac_f32_e32 v19, v36, v36
	v_fmac_f32_e32 v20, v24, v24
	v_add_f32_e32 v19, v19, v20
	v_add_f32_e32 v18, v19, v18
	v_mul_f32_e32 v19, v41, v41
	v_mul_f32_e32 v20, v39, v39
	v_fmac_f32_e32 v19, v40, v40
	v_fmac_f32_e32 v20, v38, v38
	v_add_f32_e32 v19, v19, v20
	v_add_f32_e32 v18, v19, v18
	v_mov_b32_e32 v19, v18
	s_nop 1
	v_permlane16_swap_b32_e32 v18, v19
	v_add_f32_e32 v18, v18, v19
	v_mov_b32_e32 v19, v18
	s_nop 1
	v_permlane32_swap_b32_e32 v18, v19
	v_add_f32_e32 v18, v18, v19
	v_fmamk_f32 v18, v18, 0x3c800000, v223
	v_rsq_f32_e32 v42, v18
	v_mov_b64_e32 v[18:19], v[162:163]
	v_mov_b64_e32 v[20:21], 0
	v_pk_mul_f32 v[26:27], v[26:27], v[42:43] op_sel_hi:[1,0]
	v_pk_mul_f32 v[20:21], v[30:31], v[42:43] op_sel_hi:[1,0]
	v_pk_mul_f32 v[24:25], v[24:25], v[42:43] op_sel_hi:[1,0]
	v_pk_mul_f32 v[22:23], v[32:33], v[42:43] op_sel_hi:[1,0]
	v_pk_mul_f32 v[34:35], v[142:143], v[20:21]
	v_pk_mul_f32 v[20:21], v[28:29], v[42:43] op_sel_hi:[1,0]
	v_pk_mul_f32 v[30:31], v[138:139], v[26:27]
	v_pk_mul_f32 v[28:29], v[36:37], v[42:43] op_sel_hi:[1,0]
	v_pk_mul_f32 v[26:27], v[136:137], v[24:25]
	v_pk_mul_f32 v[32:33], v[40:41], v[42:43] op_sel_hi:[1,0]
	v_pk_mul_f32 v[24:25], v[38:39], v[42:43] op_sel_hi:[1,0]
	v_pk_mul_f32 v[22:23], v[144:145], v[22:23]
	v_pk_mul_f32 v[20:21], v[140:141], v[20:21]
	v_pk_mul_f32 v[28:29], v[134:135], v[28:29]
	v_pk_mul_f32 v[24:25], v[132:133], v[24:25]
	s_and_b64 vcc, exec, s[42:43]
	v_pk_mul_f32 v[32:33], v[130:131], v[32:33]
	s_cbranch_vccnz .LBB0_674
	v_add_u32_e32 v36, 0xa0, v216
	v_ashrrev_i32_e32 v36, 6, v36
	v_cvt_f32_i32_e32 v43, v36
	v_mul_f32_e32 v36, v0, v43
	v_mul_f32_e32 v37, v165, v43
	v_mul_f32_e32 v40, v167, v43
	v_floor_f32_e32 v36, v36
	v_floor_f32_e32 v37, v37
	v_floor_f32_e32 v40, v40
	v_mul_f32_e32 v46, v169, v43
	v_fma_f32 v38, v0, v43, -v36
	v_fma_f32 v39, v165, v43, -v37
	v_fma_f32 v40, v167, v43, -v40
	v_floor_f32_e32 v46, v46
	v_sin_f32_e32 v36, v38
	v_sin_f32_e32 v37, v39
	v_cos_f32_e32 v45, v40
	v_sin_f32_e32 v48, v40
	v_fma_f32 v43, v169, v43, -v46
	v_cos_f32_e32 v38, v38
	v_cos_f32_e32 v39, v39
	v_sin_f32_e32 v47, v43
	v_cos_f32_e32 v46, v43
	v_pk_mul_f32 v[40:41], v[36:37], v[30:31]
	v_mul_f32_e32 v44, v48, v20
	v_mul_f32_e32 v50, v45, v20
	v_mov_b32_e32 v20, v23
	v_pk_mul_f32 v[30:31], v[38:39], v[30:31]
	v_mul_f32_e32 v42, v45, v22
	v_mul_f32_e32 v48, v48, v22
	v_pk_mul_f32 v[22:23], v[46:47], v[20:21]
	v_pk_fma_f32 v[38:39], v[38:39], v[34:35], v[40:41] neg_lo:[0,0,1] neg_hi:[0,0,1]
	v_floor_f32_e32 v40, v102
	v_mov_b32_e32 v43, v22
	v_mov_b32_e32 v45, v23
	v_mov_b32_e32 v22, v47
	v_mov_b32_e32 v23, v46
	v_pk_fma_f32 v[30:31], v[36:37], v[34:35], v[30:31]
	v_floor_f32_e32 v34, v104
	v_fma_f32 v40, v167, v100, -v40
	v_floor_f32_e32 v46, v101
	v_pk_mul_f32 v[20:21], v[22:23], v[20:21]
	v_pk_add_f32 v[22:23], v[42:43], v[44:45] neg_lo:[0,1] neg_hi:[0,1]
	v_fma_f32 v35, v0, v100, -v34
	v_cos_f32_e32 v43, v40
	v_sin_f32_e32 v45, v40
	v_fma_f32 v46, v169, v100, -v46
	v_sin_f32_e32 v34, v35
	v_cos_f32_e32 v36, v35
	v_floor_f32_e32 v35, v103
	v_sin_f32_e32 v47, v46
	v_cos_f32_e32 v46, v46
	v_fma_f32 v37, v165, v100, -v35
	v_mov_b32_e32 v49, v20
	v_mov_b32_e32 v51, v21
	v_sin_f32_e32 v35, v37
	v_pk_add_f32 v[20:21], v[48:49], v[50:51]
	v_cos_f32_e32 v37, v37
	v_mul_f32_e32 v44, v45, v24
	v_mul_f32_e32 v50, v43, v24
	v_mov_b32_e32 v24, v27
	v_mul_f32_e32 v42, v43, v26
	v_mul_f32_e32 v48, v45, v26
	v_pk_mul_f32 v[26:27], v[46:47], v[24:25]
	v_pk_mul_f32 v[40:41], v[34:35], v[32:33]
	v_mov_b32_e32 v43, v26
	v_mov_b32_e32 v45, v27
	v_mov_b32_e32 v26, v47
	v_mov_b32_e32 v27, v46
	v_pk_mul_f32 v[24:25], v[26:27], v[24:25]
	v_pk_mul_f32 v[32:33], v[36:37], v[32:33]
	v_mov_b32_e32 v49, v24
	v_mov_b32_e32 v51, v25
	v_pk_fma_f32 v[36:37], v[36:37], v[28:29], v[40:41] neg_lo:[0,0,1] neg_hi:[0,0,1]
	v_pk_add_f32 v[26:27], v[42:43], v[44:45] neg_lo:[0,1] neg_hi:[0,1]
	v_pk_fma_f32 v[32:33], v[34:35], v[28:29], v[32:33]
	v_pk_add_f32 v[24:25], v[48:49], v[50:51]
	v_mov_b32_e32 v34, v38
	v_mov_b32_e32 v35, v39
	v_mov_b32_e32 v28, v36
	v_mov_b32_e32 v29, v37
.LBB0_674:
	s_mov_b32 s2, 0x28000
	v_add_co_u32_e32 v18, vcc, s2, v18
	v_pk_mul_f32 v[22:23], v[22:23], s[12:13] op_sel_hi:[1,0]
	v_pk_mul_f32 v[34:35], v[34:35], s[12:13] op_sel_hi:[1,0]
	v_pk_mul_f32 v[20:21], v[20:21], s[12:13] op_sel_hi:[1,0]
	v_addc_co_u32_e32 v19, vcc, 0, v19, vcc
	v_pk_mul_f32 v[30:31], v[30:31], s[12:13] op_sel_hi:[1,0]
	v_pk_mul_f32 v[26:27], v[26:27], s[12:13] op_sel_hi:[1,0]
	v_pk_mul_f32 v[28:29], v[28:29], s[12:13] op_sel_hi:[1,0]
	v_pk_mul_f32 v[24:25], v[24:25], s[12:13] op_sel_hi:[1,0]
	v_cvt_pk_bf16_f32 v240, v34, v35
	v_cvt_pk_bf16_f32 v241, v22, v23
	v_mbcnt_lo_u32_b32 v252, -1, 0
	v_mbcnt_hi_u32_b32 v252, -1, v252
	v_bfe_u32 v252, v252, 4, 1
	v_mul_u32_u24_e32 v252, 24, v252
	v_mov_b32_e32 v253, 0
	v_lshl_add_u64 v[248:249], v[18:19], 0, v[252:253]
	v_cvt_pk_bf16_f32 v242, v30, v31
	v_cvt_pk_bf16_f32 v243, v20, v21
	s_nop 1
	v_permlane16_swap_b32_e32 v240, v242
	v_permlane16_swap_b32_e32 v241, v243
	global_store_dwordx4 v[248:249], v[240:243], off
	v_cvt_pk_bf16_f32 v244, v28, v29
	v_cvt_pk_bf16_f32 v245, v26, v27
	v_pk_fma_f32 v[16:17], v[16:17], v[164:165], v[160:161] op_sel_hi:[1,0,1]
	v_pk_fma_f32 v[14:15], v[14:15], v[164:165], v[158:159] op_sel_hi:[1,0,1]
	v_pk_mul_f32 v[32:33], v[32:33], s[12:13] op_sel_hi:[1,0]
	v_cvt_pk_bf16_f32 v246, v32, v33
	v_cvt_pk_bf16_f32 v247, v24, v25
	v_pk_fma_f32 v[24:25], v[2:3], v[164:165], v[146:147] op_sel_hi:[1,0,1]
	v_mul_f32_e32 v2, v15, v15
	v_mul_f32_e32 v3, v17, v17
	v_pk_fma_f32 v[12:13], v[12:13], v[164:165], v[156:157] op_sel_hi:[1,0,1]
	v_pk_fma_f32 v[10:11], v[10:11], v[164:165], v[154:155] op_sel_hi:[1,0,1]
	v_fmac_f32_e32 v2, v14, v14
	v_fmac_f32_e32 v3, v16, v16
	v_pk_fma_f32 v[22:23], v[6:7], v[164:165], v[150:151] op_sel_hi:[1,0,1]
	v_add_f32_e32 v2, v2, v3
	v_mul_f32_e32 v3, v11, v11
	v_mul_f32_e32 v6, v13, v13
	v_fmac_f32_e32 v3, v10, v10
	v_fmac_f32_e32 v6, v12, v12
	v_pk_fma_f32 v[8:9], v[8:9], v[164:165], v[152:153] op_sel_hi:[1,0,1]
	v_add_f32_e32 v3, v3, v6
	v_add_f32_e32 v2, v2, v3
	v_mul_f32_e32 v3, v23, v23
	v_mul_f32_e32 v6, v9, v9
	v_fmac_f32_e32 v3, v22, v22
	v_fmac_f32_e32 v6, v8, v8
	v_pk_fma_f32 v[4:5], v[4:5], v[164:165], v[148:149] op_sel_hi:[1,0,1]
	v_add_f32_e32 v3, v3, v6
	v_add_f32_e32 v2, v3, v2
	v_mul_f32_e32 v3, v25, v25
	v_mul_f32_e32 v6, v5, v5
	v_fmac_f32_e32 v3, v24, v24
	v_fmac_f32_e32 v6, v4, v4
	v_add_f32_e32 v3, v3, v6
	v_add_f32_e32 v2, v3, v2
	v_mov_b32_e32 v3, v2
	s_nop 1
	v_permlane16_swap_b32_e32 v2, v3
	v_add_f32_e32 v2, v2, v3
	v_mov_b32_e32 v3, v2
	s_nop 1
	v_permlane32_swap_b32_e32 v2, v3
	v_add_f32_e32 v2, v2, v3
	v_fmamk_f32 v2, v2, 0x3c800000, v223
	v_rsq_f32_e32 v26, v2
	v_mov_b64_e32 v[2:3], 0
	s_nop 1
	v_permlane16_swap_b32_e32 v244, v246
	v_permlane16_swap_b32_e32 v245, v247
	global_store_dwordx4 v[248:249], v[244:247], off offset:64
	v_pk_mul_f32 v[10:11], v[10:11], v[26:27] op_sel_hi:[1,0]
	v_pk_mul_f32 v[2:3], v[14:15], v[26:27] op_sel_hi:[1,0]
	v_pk_mul_f32 v[6:7], v[16:17], v[26:27] op_sel_hi:[1,0]
	v_pk_mul_f32 v[16:17], v[142:143], v[2:3]
	v_pk_mul_f32 v[2:3], v[12:13], v[26:27] op_sel_hi:[1,0]
	v_pk_mul_f32 v[12:13], v[138:139], v[10:11]
	v_pk_mul_f32 v[10:11], v[22:23], v[26:27] op_sel_hi:[1,0]
	v_pk_mul_f32 v[8:9], v[8:9], v[26:27] op_sel_hi:[1,0]
	v_pk_mul_f32 v[14:15], v[24:25], v[26:27] op_sel_hi:[1,0]
	v_pk_mul_f32 v[4:5], v[4:5], v[26:27] op_sel_hi:[1,0]
	v_pk_mul_f32 v[6:7], v[144:145], v[6:7]
	v_pk_mul_f32 v[2:3], v[140:141], v[2:3]
	v_pk_mul_f32 v[8:9], v[136:137], v[8:9]
	v_pk_mul_f32 v[10:11], v[134:135], v[10:11]
	v_pk_mul_f32 v[4:5], v[132:133], v[4:5]
	s_and_b64 vcc, exec, s[42:43]
	v_pk_mul_f32 v[14:15], v[130:131], v[14:15]
	s_cbranch_vccnz .LBB0_676
	v_add_u32_e32 v18, 0xb0, v216
	v_ashrrev_i32_e32 v18, 6, v18
	v_cvt_f32_i32_e32 v25, v18
	v_mul_f32_e32 v18, v0, v25
	v_mul_f32_e32 v19, v165, v25
	v_floor_f32_e32 v18, v18
	v_floor_f32_e32 v19, v19
	v_fma_f32 v20, v0, v25, -v18
	v_fma_f32 v21, v165, v25, -v19
	v_sin_f32_e32 v18, v20
	v_cos_f32_e32 v20, v20
	v_sin_f32_e32 v19, v21
	v_cos_f32_e32 v21, v21
	v_mul_f32_e32 v22, v167, v25
	v_floor_f32_e32 v22, v22
	v_mul_f32_e32 v28, v169, v25
	v_fma_f32 v22, v167, v25, -v22
	v_floor_f32_e32 v28, v28
	v_cos_f32_e32 v27, v22
	v_sin_f32_e32 v30, v22
	v_fma_f32 v25, v169, v25, -v28
	v_pk_mul_f32 v[22:23], v[18:19], v[12:13]
	v_pk_mul_f32 v[12:13], v[20:21], v[12:13]
	v_sin_f32_e32 v29, v25
	v_cos_f32_e32 v28, v25
	v_pk_fma_f32 v[20:21], v[20:21], v[16:17], v[22:23] neg_lo:[0,0,1] neg_hi:[0,0,1]
	v_pk_fma_f32 v[12:13], v[18:19], v[16:17], v[12:13]
	v_floor_f32_e32 v16, v88
	v_fma_f32 v0, v0, v84, -v16
	v_mul_f32_e32 v26, v30, v2
	v_mul_f32_e32 v32, v27, v2
	v_mov_b32_e32 v2, v7
	v_sin_f32_e32 v16, v0
	v_cos_f32_e32 v18, v0
	v_floor_f32_e32 v0, v87
	v_mul_f32_e32 v24, v27, v6
	v_mul_f32_e32 v30, v30, v6
	v_pk_mul_f32 v[6:7], v[28:29], v[2:3]
	v_fma_f32 v0, v165, v84, -v0
	v_mov_b32_e32 v25, v6
	v_mov_b32_e32 v27, v7
	v_mov_b32_e32 v6, v29
	v_mov_b32_e32 v7, v28
	v_sin_f32_e32 v17, v0
	v_cos_f32_e32 v19, v0
	v_floor_f32_e32 v0, v86
	v_pk_mul_f32 v[2:3], v[6:7], v[2:3]
	v_pk_add_f32 v[6:7], v[24:25], v[26:27] neg_lo:[0,1] neg_hi:[0,1]
	v_fma_f32 v0, v167, v84, -v0
	v_floor_f32_e32 v27, v85
	v_cos_f32_e32 v25, v0
	v_sin_f32_e32 v0, v0
	v_fma_f32 v27, v169, v84, -v27
	v_sin_f32_e32 v29, v27
	v_cos_f32_e32 v28, v27
	v_mov_b32_e32 v31, v2
	v_mov_b32_e32 v33, v3
	v_pk_add_f32 v[2:3], v[30:31], v[32:33]
	v_mul_f32_e32 v26, v0, v4
	v_mul_f32_e32 v32, v25, v4
	v_mov_b32_e32 v4, v9
	v_mul_f32_e32 v24, v25, v8
	v_mul_f32_e32 v30, v0, v8
	v_pk_mul_f32 v[8:9], v[28:29], v[4:5]
	v_pk_mul_f32 v[22:23], v[16:17], v[14:15]
	v_mov_b32_e32 v25, v8
	v_mov_b32_e32 v27, v9
	v_mov_b32_e32 v8, v29
	v_mov_b32_e32 v9, v28
	v_pk_mul_f32 v[4:5], v[8:9], v[4:5]
	v_pk_mul_f32 v[14:15], v[18:19], v[14:15]
	v_mov_b32_e32 v31, v4
	v_mov_b32_e32 v33, v5
	v_pk_fma_f32 v[18:19], v[18:19], v[10:11], v[22:23] neg_lo:[0,0,1] neg_hi:[0,0,1]
	v_pk_add_f32 v[8:9], v[24:25], v[26:27] neg_lo:[0,1] neg_hi:[0,1]
	v_pk_fma_f32 v[14:15], v[16:17], v[10:11], v[14:15]
	v_pk_add_f32 v[4:5], v[30:31], v[32:33]
	v_mov_b32_e32 v16, v20
	v_mov_b32_e32 v17, v21
	v_mov_b32_e32 v10, v18
	v_mov_b32_e32 v11, v19
.LBB0_676:
	v_pk_mul_f32 v[6:7], v[6:7], s[12:13] op_sel_hi:[1,0]
	v_pk_mul_f32 v[16:17], v[16:17], s[12:13] op_sel_hi:[1,0]
	s_mov_b32 s2, 0x2c000
	v_cvt_pk_bf16_f32 v240, v16, v17
	v_cvt_pk_bf16_f32 v241, v6, v7
	v_add_co_u32_e32 v6, vcc, s2, v162
	v_pk_mul_f32 v[2:3], v[2:3], s[12:13] op_sel_hi:[1,0]
	v_pk_mul_f32 v[12:13], v[12:13], s[12:13] op_sel_hi:[1,0]
	v_addc_co_u32_e32 v7, vcc, 0, v163, vcc
	v_pk_mul_f32 v[8:9], v[8:9], s[12:13] op_sel_hi:[1,0]
	v_pk_mul_f32 v[10:11], v[10:11], s[12:13] op_sel_hi:[1,0]
	v_mbcnt_lo_u32_b32 v252, -1, 0
	v_mbcnt_hi_u32_b32 v252, -1, v252
	v_bfe_u32 v252, v252, 4, 1
	v_mul_u32_u24_e32 v252, 24, v252
	v_mov_b32_e32 v253, 0
	v_lshl_add_u64 v[248:249], v[6:7], 0, v[252:253]
	v_cvt_pk_bf16_f32 v242, v12, v13
	v_cvt_pk_bf16_f32 v243, v2, v3
	s_nop 1
	v_permlane16_swap_b32_e32 v240, v242
	v_permlane16_swap_b32_e32 v241, v243
	global_store_dwordx4 v[248:249], v[240:243], off
	v_cvt_pk_bf16_f32 v244, v10, v11
	v_cvt_pk_bf16_f32 v245, v8, v9
	v_pk_mul_f32 v[4:5], v[4:5], s[12:13] op_sel_hi:[1,0]
	v_pk_mul_f32 v[14:15], v[14:15], s[12:13] op_sel_hi:[1,0]
	v_cvt_pk_bf16_f32 v246, v14, v15
	v_cvt_pk_bf16_f32 v247, v4, v5
	s_nop 1
	v_permlane16_swap_b32_e32 v244, v246
	v_permlane16_swap_b32_e32 v245, v247
	global_store_dwordx4 v[248:249], v[244:247], off offset:64
	s_andn2_b64 vcc, exec, s[40:41]
	s_mov_b64 s[2:3], -1
	s_cbranch_vccnz .LBB0_592
